# row passes: output stores write-through (sc0 sc1) to shrink the L2 write-back at the cross-XCC barrier after st10
# baseline (speedup 1.0000x reference)
.LBB0_562:
	s_lshl_b32 s6, s24, 3
	s_ashr_i32 s7, s6, 31
	v_lshlrev_b32_e32 v49, 2, v116
	s_lshl_b64 s[10:11], s[6:7], 10
	v_mov_b32_e32 v217, s11
	v_or_b32_e32 v216, s10, v49
	v_lshlrev_b64 v[66:67], 1, v[216:217]
	v_lshl_add_u64 v[218:219], s[8:9], 0, v[66:67]
	v_lshl_add_u64 v[66:67], s[38:39], 0, v[66:67]
	global_load_dwordx2 v[90:91], v[218:219], off
	global_load_dwordx2 v[224:225], v[218:219], off offset:512
	global_load_dwordx2 v[222:223], v[218:219], off offset:1024
	global_load_dwordx2 v[220:221], v[218:219], off offset:1536
	global_load_dwordx2 v[86:87], v[66:67], off
	global_load_dwordx2 v[88:89], v[66:67], off offset:512
	global_load_dwordx2 v[92:93], v[66:67], off offset:1024
	global_load_dwordx2 v[230:231], v[66:67], off offset:1536
	s_or_b32 s10, s6, 1
	s_ashr_i32 s11, s10, 31
	s_lshl_b64 s[10:11], s[10:11], 10
	v_or_b32_e32 v196, s10, v49
	s_or_b32 s10, s6, 2
	v_mov_b32_e32 v197, s11
	s_ashr_i32 s11, s10, 31
	s_lshl_b64 s[10:11], s[10:11], 10
	v_or_b32_e32 v176, s10, v49
	s_or_b32 s10, s6, 3
	v_mov_b32_e32 v177, s11
	s_ashr_i32 s11, s10, 31
	s_lshl_b64 s[10:11], s[10:11], 10
	v_lshlrev_b64 v[66:67], 1, v[196:197]
	v_or_b32_e32 v156, s10, v49
	s_or_b32 s10, s6, 4
	v_lshl_add_u64 v[198:199], s[8:9], 0, v[66:67]
	v_lshl_add_u64 v[66:67], s[38:39], 0, v[66:67]
	v_mov_b32_e32 v157, s11
	s_ashr_i32 s11, s10, 31
	global_load_dwordx2 v[206:207], v[198:199], off
	global_load_dwordx2 v[204:205], v[198:199], off offset:512
	global_load_dwordx2 v[202:203], v[198:199], off offset:1024
	global_load_dwordx2 v[200:201], v[198:199], off offset:1536
	global_load_dwordx2 v[214:215], v[66:67], off
	global_load_dwordx2 v[212:213], v[66:67], off offset:512
	global_load_dwordx2 v[210:211], v[66:67], off offset:1024
	global_load_dwordx2 v[208:209], v[66:67], off offset:1536
	v_lshlrev_b64 v[66:67], 1, v[176:177]
	s_lshl_b64 s[10:11], s[10:11], 10
	v_lshl_add_u64 v[178:179], s[8:9], 0, v[66:67]
	v_lshl_add_u64 v[66:67], s[38:39], 0, v[66:67]
	v_or_b32_e32 v134, s10, v49
	s_or_b32 s10, s6, 5
	global_load_dwordx2 v[186:187], v[178:179], off
	global_load_dwordx2 v[184:185], v[178:179], off offset:512
	global_load_dwordx2 v[182:183], v[178:179], off offset:1024
	global_load_dwordx2 v[180:181], v[178:179], off offset:1536
	global_load_dwordx2 v[194:195], v[66:67], off
	global_load_dwordx2 v[192:193], v[66:67], off offset:512
	global_load_dwordx2 v[190:191], v[66:67], off offset:1024
	global_load_dwordx2 v[188:189], v[66:67], off offset:1536
	v_lshlrev_b64 v[66:67], 1, v[156:157]
	v_mov_b32_e32 v135, s11
	s_ashr_i32 s11, s10, 31
	v_lshl_add_u64 v[158:159], s[8:9], 0, v[66:67]
	v_lshl_add_u64 v[66:67], s[38:39], 0, v[66:67]
	s_lshl_b64 s[10:11], s[10:11], 10
	global_load_dwordx2 v[166:167], v[158:159], off
	global_load_dwordx2 v[164:165], v[158:159], off offset:512
	global_load_dwordx2 v[162:163], v[158:159], off offset:1024
	global_load_dwordx2 v[160:161], v[158:159], off offset:1536
	global_load_dwordx2 v[174:175], v[66:67], off
	global_load_dwordx2 v[172:173], v[66:67], off offset:512
	global_load_dwordx2 v[170:171], v[66:67], off offset:1024
	global_load_dwordx2 v[168:169], v[66:67], off offset:1536
	v_lshlrev_b64 v[66:67], 1, v[134:135]
	v_or_b32_e32 v114, s10, v49
	s_or_b32 s10, s6, 6
	v_lshl_add_u64 v[136:137], s[8:9], 0, v[66:67]
	v_lshl_add_u64 v[66:67], s[38:39], 0, v[66:67]
	v_mov_b32_e32 v115, s11
	s_ashr_i32 s11, s10, 31
	global_load_dwordx2 v[146:147], v[136:137], off
	global_load_dwordx2 v[142:143], v[136:137], off offset:512
	global_load_dwordx2 v[140:141], v[136:137], off offset:1024
	global_load_dwordx2 v[138:139], v[136:137], off offset:1536
	global_load_dwordx2 v[154:155], v[66:67], off
	global_load_dwordx2 v[152:153], v[66:67], off offset:512
	global_load_dwordx2 v[150:151], v[66:67], off offset:1024
	global_load_dwordx2 v[148:149], v[66:67], off offset:1536
	v_lshlrev_b64 v[66:67], 1, v[114:115]
	s_lshl_b64 s[10:11], s[10:11], 10
	v_lshl_add_u64 v[116:117], s[8:9], 0, v[66:67]
	v_lshl_add_u64 v[66:67], s[38:39], 0, v[66:67]
	v_mov_b32_e32 v95, s11
	v_or_b32_e32 v94, s10, v49
	s_or_b32 s6, s6, 7
	global_load_dwordx2 v[124:125], v[116:117], off
	global_load_dwordx2 v[122:123], v[116:117], off offset:512
	global_load_dwordx2 v[120:121], v[116:117], off offset:1024
	global_load_dwordx2 v[118:119], v[116:117], off offset:1536
	global_load_dwordx2 v[132:133], v[66:67], off
	global_load_dwordx2 v[130:131], v[66:67], off offset:512
	global_load_dwordx2 v[128:129], v[66:67], off offset:1024
	global_load_dwordx2 v[126:127], v[66:67], off offset:1536
	v_lshlrev_b64 v[66:67], 1, v[94:95]
	s_ashr_i32 s7, s6, 31
	v_lshl_add_u64 v[96:97], s[8:9], 0, v[66:67]
	v_lshl_add_u64 v[66:67], s[38:39], 0, v[66:67]
	s_lshl_b64 s[6:7], s[6:7], 10
	global_load_dwordx2 v[104:105], v[96:97], off
	global_load_dwordx2 v[102:103], v[96:97], off offset:512
	global_load_dwordx2 v[100:101], v[96:97], off offset:1024
	global_load_dwordx2 v[98:99], v[96:97], off offset:1536
	global_load_dwordx2 v[112:113], v[66:67], off
	global_load_dwordx2 v[110:111], v[66:67], off offset:512
	global_load_dwordx2 v[108:109], v[66:67], off offset:1024
	global_load_dwordx2 v[106:107], v[66:67], off offset:1536
	v_mov_b32_e32 v67, s7
	v_or_b32_e32 v66, s6, v49
	v_lshlrev_b64 v[70:71], 1, v[66:67]
	v_lshl_add_u64 v[68:69], s[8:9], 0, v[70:71]
	v_lshl_add_u64 v[78:79], s[38:39], 0, v[70:71]
	global_load_dwordx2 v[76:77], v[68:69], off
	global_load_dwordx2 v[74:75], v[68:69], off offset:512
	global_load_dwordx2 v[72:73], v[68:69], off offset:1024
	global_load_dwordx2 v[70:71], v[68:69], off offset:1536
	global_load_dwordx2 v[84:85], v[78:79], off
	global_load_dwordx2 v[82:83], v[78:79], off offset:512
	global_load_dwordx2 v[80:81], v[78:79], off offset:1024
	s_nop 0
	global_load_dwordx2 v[78:79], v[78:79], off offset:1536
	v_xor_b32_e32 v144, 4, v49
	v_xor_b32_e32 v251, 32, v49
	v_xor_b32_e32 v252, 64, v49
	s_waitcnt vmcnt(0)
	v_pk_add_f32 v[20:21], v[20:21], 1.0 op_sel_hi:[1,0]
	v_pk_add_f32 v[22:23], v[22:23], 1.0 op_sel_hi:[1,0]
	v_pk_mul_f32 v[20:21], v[48:49], v[20:21] op_sel_hi:[0,1]
	v_pk_mul_f32 v[22:23], v[48:49], v[22:23] op_sel_hi:[0,1]
	s_cmp_lg_u64 s[0:1], 0
	s_cselect_b64 s[8:9], -1, 0
	s_cmp_eq_u64 s[0:1], 0
	v_and_b32_e32 v237, 0xffff0000, v86
	v_and_b32_e32 v249, 0xffff0000, v87
	v_lshlrev_b32_e32 v236, 16, v86
	v_lshlrev_b32_e32 v248, 16, v87
	v_mul_f32_e32 v86, v249, v249
	v_and_b32_e32 v243, 0xffff0000, v89
	v_and_b32_e32 v242, 0xffff0000, v88
	v_lshlrev_b32_e32 v232, 16, v92
	v_and_b32_e32 v233, 0xffff0000, v92
	v_mul_f32_e32 v92, v237, v237
	v_pk_fma_f32 v[86:87], v[248:249], v[248:249], v[86:87] op_sel_hi:[1,1,0]
	v_lshlrev_b32_e32 v241, 16, v89
	v_lshlrev_b32_e32 v240, 16, v88
	v_pk_mul_f32 v[88:89], v[242:243], v[242:243]
	v_lshlrev_b32_e32 v234, 16, v93
	v_and_b32_e32 v235, 0xffff0000, v93
	v_lshlrev_b32_e32 v229, 16, v230
	v_pk_fma_f32 v[92:93], v[236:237], v[236:237], v[92:93] op_sel_hi:[1,1,0]
	v_pk_fma_f32 v[88:89], v[240:241], v[240:241], v[88:89]
	v_and_b32_e32 v227, 0xffff0000, v230
	v_mov_b32_e32 v228, v92
	v_mov_b32_e32 v238, v86
	v_mov_b32_e32 v239, v229
	v_mul_f32_e32 v226, v227, v227
	v_pk_add_f32 v[86:87], v[92:93], v[86:87]
	v_pk_mul_f32 v[92:93], v[228:229], v[238:239]
	v_pk_add_f32 v[88:89], v[88:89], v[88:89] op_sel:[0,1] op_sel_hi:[1,0]
	v_mov_b32_e32 v87, v93
	v_mov_b32_e32 v89, v226
	v_lshlrev_b32_e32 v230, 16, v231
	v_and_b32_e32 v231, 0xffff0000, v231
	v_pk_add_f32 v[86:87], v[86:87], v[88:89]
	v_mul_f32_e32 v88, v233, v233
	v_mul_f32_e32 v92, v235, v235
	v_mul_f32_e32 v246, v230, v230
	v_mul_f32_e32 v250, v231, v231
	v_pk_fma_f32 v[88:89], v[232:233], v[232:233], v[88:89] op_sel_hi:[1,1,0]
	v_pk_fma_f32 v[92:93], v[234:235], v[234:235], v[92:93] op_sel_hi:[1,1,0]
	v_mov_b32_e32 v89, v246
	v_mov_b32_e32 v93, v250
	v_pk_add_f32 v[88:89], v[88:89], v[92:93]
	v_xor_b32_e32 v228, 8, v49
	v_pk_add_f32 v[86:87], v[86:87], v[88:89]
	v_xor_b32_e32 v250, 16, v49
	v_add_f32_e32 v86, v86, v87
	s_nop 1
	v_mov_b32_dpp v87, v86 quad_perm:[1,0,3,2] row_mask:0xf bank_mask:0xf
	v_xor_b32_e32 v246, 0x80, v49
	v_pk_mul_f32 v[88:89], v[18:19], v[22:23]
	v_and_b32_e32 v19, 0xffff0000, v91
	s_waitcnt lgkmcnt(0)
	v_add_f32_e32 v86, v86, v87
	s_nop 1
	v_mov_b32_dpp v87, v86 quad_perm:[2,3,0,1] row_mask:0xf bank_mask:0xf
	s_waitcnt lgkmcnt(0)
	v_add_f32_e32 v86, v86, v87
	s_nop 1
	v_mov_b32_dpp v87, v86 row_half_mirror row_mask:0xf bank_mask:0xf
	s_waitcnt lgkmcnt(0)
	v_add_f32_e32 v86, v86, v87
	s_nop 1
	v_mov_b32_dpp v87, v86 row_mirror row_mask:0xf bank_mask:0xf
	s_waitcnt lgkmcnt(0)
	v_add_f32_e32 v92, v86, v87
	v_pk_mul_f32 v[86:87], v[16:17], v[20:21]
	v_lshlrev_b32_e32 v16, 16, v90
	s_waitcnt lgkmcnt(0)
	s_nop 0
	v_readlane_b32 s98, v92, 32
	v_readlane_b32 s100, v92, 48
	s_nop 1
	v_mov_b32_e32 v93, s100
	v_add_f32_e32 v93, s98, v93
	v_readlane_b32 s98, v92, 0
	v_readlane_b32 s100, v92, 16
	s_nop 1
	v_mov_b32_e32 v17, s100
	v_add_f32_e32 v17, s98, v17
	v_add_f32_e32 v17, v17, v93
	s_waitcnt lgkmcnt(0)
	v_fmamk_f32 v17, v17, 0x3a800000, v247
	v_mul_f32_e32 v18, 0x4b800000, v17
	v_cmp_gt_f32_e32 vcc, s35, v17
	s_nop 1
	v_cndmask_b32_e32 v17, v17, v18, vcc
	v_rsq_f32_e32 v20, v17
	v_and_b32_e32 v17, 0xffff0000, v90
	v_lshlrev_b32_e32 v18, 16, v91
	v_mul_f32_e32 v21, 0x45800000, v20
	v_cndmask_b32_e32 v238, v20, v21, vcc
	v_pk_mul_f32 v[20:21], v[238:239], v[236:237] op_sel_hi:[0,1]
	v_pk_mul_f32 v[22:23], v[238:239], v[248:249] op_sel_hi:[0,1]
	v_pk_fma_f32 v[18:19], v[88:89], v[22:23], v[18:19]
	v_pk_fma_f32 v[16:17], v[86:87], v[20:21], v[16:17]
	v_lshl_add_u64 v[236:237], v[216:217], 2, s[0:1]
	s_cbranch_scc1 .LBB0_573
	global_store_dwordx4 v[236:237], v[16:19], off sc0 sc1
	s_cbranch_execnz .LBB0_565
.LBB0_564:
	v_cvt_pk_bf16_f32 v20, v16, v17
	v_cvt_pk_bf16_f32 v21, v18, v19
	global_store_dwordx2 v[218:219], v[20:21], off sc0 sc1
.LBB0_565:
	v_mov_b32_e32 v49, v48
	v_pk_add_f32 v[20:21], v[30:31], 1.0 op_sel_hi:[1,0]
	v_pk_add_f32 v[22:23], v[28:29], 1.0 op_sel_hi:[1,0]
	v_mov_b32_e32 v28, v48
	v_mov_b32_e32 v29, v48
	v_pk_mul_f32 v[20:21], v[28:29], v[20:21]
	v_pk_mul_f32 v[22:23], v[48:49], v[22:23]
	v_pk_mul_f32 v[92:93], v[26:27], v[20:21]
	v_pk_mul_f32 v[90:91], v[24:25], v[22:23]
	v_mov_b32_e32 v24, v241
	v_mov_b32_e32 v25, v243
	v_mov_b32_e32 v26, v238
	v_mov_b32_e32 v27, v238
	v_mov_b32_e32 v239, v238
	v_lshlrev_b32_e32 v22, 16, v225
	v_and_b32_e32 v23, 0xffff0000, v225
	v_pk_mul_f32 v[24:25], v[26:27], v[24:25]
	v_mov_b32_e32 v241, v242
	v_lshlrev_b32_e32 v20, 16, v224
	v_and_b32_e32 v21, 0xffff0000, v224
	v_pk_mul_f32 v[26:27], v[238:239], v[240:241]
	v_pk_fma_f32 v[22:23], v[92:93], v[24:25], v[22:23]
	v_cndmask_b32_e64 v24, 0, 1, s[8:9]
	v_cmp_ne_u32_e64 s[6:7], 1, v24
	s_andn2_b64 vcc, exec, s[8:9]
	v_pk_fma_f32 v[20:21], v[90:91], v[26:27], v[20:21]
	s_cbranch_vccnz .LBB0_574
	global_store_dwordx4 v[236:237], v[20:23], off offset:1024 sc0 sc1
	s_cbranch_execnz .LBB0_568
.LBB0_567:
	v_cvt_pk_bf16_f32 v24, v20, v21
	v_cvt_pk_bf16_f32 v25, v22, v23
	global_store_dwordx2 v[218:219], v[24:25], off offset:512 sc0 sc1
.LBB0_568:
	v_pk_add_f32 v[24:25], v[38:39], 1.0 op_sel_hi:[1,0]
	v_pk_add_f32 v[26:27], v[36:37], 1.0 op_sel_hi:[1,0]
	v_mov_b32_e32 v28, v48
	v_mov_b32_e32 v29, v48
	v_pk_mul_f32 v[24:25], v[28:29], v[24:25]
	v_pk_mul_f32 v[26:27], v[48:49], v[26:27]
	v_mov_b32_e32 v30, v238
	v_mov_b32_e32 v31, v238
	v_pk_mul_f32 v[36:37], v[34:35], v[24:25]
	v_pk_mul_f32 v[32:33], v[32:33], v[26:27]
	v_lshlrev_b32_e32 v24, 16, v222
	v_and_b32_e32 v25, 0xffff0000, v222
	v_lshlrev_b32_e32 v26, 16, v223
	v_and_b32_e32 v27, 0xffff0000, v223
	v_pk_mul_f32 v[28:29], v[238:239], v[232:233]
	v_pk_mul_f32 v[30:31], v[30:31], v[234:235]
	s_and_b64 vcc, exec, s[6:7]
	v_pk_fma_f32 v[26:27], v[36:37], v[30:31], v[26:27]
	v_pk_fma_f32 v[24:25], v[32:33], v[28:29], v[24:25]
	s_cbranch_vccnz .LBB0_575
	global_store_dwordx4 v[236:237], v[24:27], off offset:2048 sc0 sc1
	s_cbranch_execnz .LBB0_571
.LBB0_570:
	v_cvt_pk_bf16_f32 v28, v24, v25
	v_cvt_pk_bf16_f32 v29, v26, v27
	global_store_dwordx2 v[218:219], v[28:29], off offset:1024 sc0 sc1
.LBB0_571:
	v_pk_add_f32 v[30:31], v[44:45], 1.0 op_sel_hi:[1,0]
	v_pk_add_f32 v[28:29], v[46:47], 1.0 op_sel_hi:[1,0]
	v_mov_b32_e32 v34, v48
	v_mov_b32_e32 v35, v48
	v_pk_mul_f32 v[30:31], v[48:49], v[30:31]
	v_pk_mul_f32 v[28:29], v[34:35], v[28:29]
	v_pk_mul_f32 v[34:35], v[40:41], v[30:31]
	v_mov_b32_e32 v40, v238
	v_mov_b32_e32 v41, v238
	v_mov_b32_e32 v226, v229
	v_pk_mul_f32 v[38:39], v[42:43], v[28:29]
	v_lshlrev_b32_e32 v28, 16, v220
	v_and_b32_e32 v29, 0xffff0000, v220
	v_lshlrev_b32_e32 v30, 16, v221
	v_and_b32_e32 v31, 0xffff0000, v221
	v_pk_mul_f32 v[40:41], v[230:231], v[40:41]
	v_pk_mul_f32 v[42:43], v[226:227], v[238:239]
	v_pk_fma_f32 v[30:31], v[38:39], v[40:41], v[30:31]
	s_and_b64 vcc, exec, s[6:7]
	v_pk_fma_f32 v[28:29], v[34:35], v[42:43], v[28:29]
	s_cbranch_vccnz .LBB0_576
	s_mov_b64 s[8:9], 0
	global_store_dwordx4 v[236:237], v[28:31], off offset:3072 sc0 sc1
	s_branch .LBB0_577

.LBB0_577:
	v_mov_b32_e32 v236, 0x2000
	v_mov_b32_e32 v237, 1
	v_mov_b32_e32 v239, 0x9000
	s_andn2_b64 vcc, exec, s[8:9]
	s_cbranch_vccnz .LBB0_579
	v_cvt_pk_bf16_f32 v40, v28, v29
	v_cvt_pk_bf16_f32 v41, v30, v31
	global_store_dwordx2 v[218:219], v[40:41], off offset:1536 sc0 sc1
.LBB0_579:
	s_and_b64 vcc, exec, s[4:5]
	s_cbranch_vccnz .LBB0_581
	v_mul_f32_e32 v40, v17, v17
	v_mul_f32_e32 v41, v19, v19
	v_fmac_f32_e32 v40, v16, v16
	v_fmac_f32_e32 v41, v18, v18
	v_add_f32_e32 v40, v40, v41
	v_mul_f32_e32 v41, v21, v21
	v_mul_f32_e32 v42, v23, v23
	v_fmac_f32_e32 v41, v20, v20
	v_fmac_f32_e32 v42, v22, v22
	v_add_f32_e32 v41, v41, v42
	v_add_f32_e32 v40, v40, v41
	v_mul_f32_e32 v41, v25, v25
	v_mul_f32_e32 v42, v27, v27
	v_fmac_f32_e32 v41, v24, v24
	v_fmac_f32_e32 v42, v26, v26
	v_add_f32_e32 v41, v41, v42
	v_add_f32_e32 v40, v41, v40
	v_mul_f32_e32 v41, v29, v29
	v_mul_f32_e32 v42, v31, v31
	v_fmac_f32_e32 v41, v28, v28
	v_fmac_f32_e32 v42, v30, v30
	v_add_f32_e32 v41, v41, v42
	v_add_f32_e32 v40, v41, v40
	s_nop 1
	v_mov_b32_dpp v41, v40 quad_perm:[1,0,3,2] row_mask:0xf bank_mask:0xf
	s_waitcnt lgkmcnt(0)
	v_add_f32_e32 v40, v40, v41
	s_nop 1
	v_mov_b32_dpp v41, v40 quad_perm:[2,3,0,1] row_mask:0xf bank_mask:0xf
	s_waitcnt lgkmcnt(0)
	v_add_f32_e32 v40, v40, v41
	s_nop 1
	v_mov_b32_dpp v41, v40 row_half_mirror row_mask:0xf bank_mask:0xf
	s_waitcnt lgkmcnt(0)
	v_add_f32_e32 v40, v40, v41
	s_nop 1
	v_mov_b32_dpp v41, v40 row_mirror row_mask:0xf bank_mask:0xf
	s_waitcnt lgkmcnt(0)
	v_add_f32_e32 v40, v40, v41
	s_waitcnt lgkmcnt(0)
	s_nop 0
	v_readlane_b32 s98, v40, 32
	v_readlane_b32 s100, v40, 48
	s_nop 1
	v_mov_b32_e32 v41, s100
	v_add_f32_e32 v41, s98, v41
	v_readlane_b32 s98, v40, 0
	v_readlane_b32 s100, v40, 16
	s_nop 1
	v_mov_b32_e32 v40, s100
	v_add_f32_e32 v40, s98, v40
	v_add_f32_e32 v40, v40, v41
	s_waitcnt lgkmcnt(0)
	v_fmamk_f32 v40, v40, 0x3a800000, v247
	v_mul_f32_e32 v41, 0x4b800000, v40
	v_cmp_gt_f32_e32 vcc, s35, v40
	s_nop 1
	v_cndmask_b32_e32 v40, v40, v41, vcc
	v_rsq_f32_e32 v42, v40
	v_lshl_add_u64 v[40:41], v[216:217], 1, s[42:43]
	v_mul_f32_e32 v43, 0x45800000, v42
	v_cndmask_b32_e32 v42, v42, v43, vcc
	v_pk_mul_f32 v[16:17], v[16:17], v[42:43] op_sel_hi:[1,0]
	v_pk_mul_f32 v[18:19], v[18:19], v[42:43] op_sel_hi:[1,0]
	v_pk_mul_f32 v[20:21], v[20:21], v[42:43] op_sel_hi:[1,0]
	v_pk_mul_f32 v[22:23], v[22:23], v[42:43] op_sel_hi:[1,0]
	v_pk_fma_f32 v[18:19], v[54:55], v[18:19], v[2:3]
	v_pk_fma_f32 v[16:17], v[52:53], v[16:17], v[0:1]
	v_pk_fma_f32 v[22:23], v[56:57], v[22:23], v[6:7]
	v_pk_fma_f32 v[20:21], v[50:51], v[20:21], v[4:5]
	v_cvt_pk_bf16_f32 v16, v16, v17
	v_cvt_pk_bf16_f32 v17, v18, v19
	v_cvt_pk_bf16_f32 v18, v20, v21
	v_cvt_pk_bf16_f32 v19, v22, v23
	global_store_dwordx2 v[40:41], v[16:17], off sc0 sc1
	global_store_dwordx2 v[40:41], v[18:19], off offset:512 sc0 sc1
	v_pk_mul_f32 v[16:17], v[24:25], v[42:43] op_sel_hi:[1,0]
	v_pk_mul_f32 v[18:19], v[26:27], v[42:43] op_sel_hi:[1,0]
	v_pk_fma_f32 v[16:17], v[60:61], v[16:17], v[8:9]
	v_pk_fma_f32 v[18:19], v[62:63], v[18:19], v[10:11]
	v_cvt_pk_bf16_f32 v16, v16, v17
	v_cvt_pk_bf16_f32 v17, v18, v19
	global_store_dwordx2 v[40:41], v[16:17], off offset:1024 sc0 sc1
	v_pk_mul_f32 v[16:17], v[28:29], v[42:43] op_sel_hi:[1,0]
	v_pk_mul_f32 v[18:19], v[30:31], v[42:43] op_sel_hi:[1,0]
	v_pk_fma_f32 v[16:17], v[58:59], v[16:17], v[12:13]
	v_pk_fma_f32 v[18:19], v[64:65], v[18:19], v[14:15]
	v_cvt_pk_bf16_f32 v16, v16, v17
	v_cvt_pk_bf16_f32 v17, v18, v19
	global_store_dwordx2 v[40:41], v[16:17], off offset:1536 sc0 sc1
.LBB0_581:
	v_and_b32_e32 v17, 0xffff0000, v214
	v_and_b32_e32 v19, 0xffff0000, v215
	v_lshlrev_b32_e32 v16, 16, v214
	v_lshlrev_b32_e32 v18, 16, v215
	v_mul_f32_e32 v20, v19, v19
	v_and_b32_e32 v23, 0xffff0000, v213
	v_and_b32_e32 v22, 0xffff0000, v212
	v_and_b32_e32 v29, 0xffff0000, v208
	v_mul_f32_e32 v28, v17, v17
	v_pk_fma_f32 v[42:43], v[18:19], v[18:19], v[20:21] op_sel_hi:[1,1,0]
	v_lshlrev_b32_e32 v21, 16, v213
	v_lshlrev_b32_e32 v20, 16, v212
	v_pk_mul_f32 v[24:25], v[22:23], v[22:23]
	v_lshlrev_b32_e32 v31, 16, v208
	v_pk_fma_f32 v[46:47], v[16:17], v[16:17], v[28:29] op_sel_hi:[1,1,0]
	v_pk_fma_f32 v[44:45], v[20:21], v[20:21], v[24:25]
	v_mov_b32_e32 v30, v46
	v_mov_b32_e32 v48, v42
	v_mov_b32_e32 v49, v31
	v_and_b32_e32 v25, 0xffff0000, v210
	v_mul_f32_e32 v208, v29, v29
	v_pk_add_f32 v[42:43], v[46:47], v[42:43]
	v_pk_mul_f32 v[46:47], v[30:31], v[48:49]
	v_pk_add_f32 v[44:45], v[44:45], v[44:45] op_sel:[0,1] op_sel_hi:[1,0]
	v_lshlrev_b32_e32 v24, 16, v210
	v_and_b32_e32 v27, 0xffff0000, v211
	v_mov_b32_e32 v43, v47
	v_mov_b32_e32 v45, v208
	v_mul_f32_e32 v28, v25, v25
	v_lshlrev_b32_e32 v26, 16, v211
	v_lshlrev_b32_e32 v40, 16, v209
	v_and_b32_e32 v41, 0xffff0000, v209
	v_pk_add_f32 v[42:43], v[42:43], v[44:45]
	v_pk_fma_f32 v[44:45], v[24:25], v[24:25], v[28:29] op_sel_hi:[1,1,0]
	v_mul_f32_e32 v28, v27, v27
	v_mul_f32_e32 v209, v40, v40
	v_mul_f32_e32 v210, v41, v41
	v_pk_fma_f32 v[46:47], v[26:27], v[26:27], v[28:29] op_sel_hi:[1,1,0]
	v_mov_b32_e32 v45, v209
	v_mov_b32_e32 v47, v210
	v_pk_add_f32 v[44:45], v[44:45], v[46:47]
	v_lshlrev_b32_e32 v46, 16, v207
	v_pk_add_f32 v[42:43], v[42:43], v[44:45]
	v_lshlrev_b32_e32 v44, 16, v206
	v_add_f32_e32 v28, v42, v43
	s_nop 1
	v_mov_b32_dpp v30, v28 quad_perm:[1,0,3,2] row_mask:0xf bank_mask:0xf
	v_and_b32_e32 v45, 0xffff0000, v206
	v_and_b32_e32 v47, 0xffff0000, v207
	s_waitcnt lgkmcnt(0)
	v_add_f32_e32 v28, v28, v30
	s_nop 1
	v_mov_b32_dpp v30, v28 quad_perm:[2,3,0,1] row_mask:0xf bank_mask:0xf
	s_waitcnt lgkmcnt(0)
	v_add_f32_e32 v28, v28, v30
	s_nop 1
	v_mov_b32_dpp v30, v28 row_half_mirror row_mask:0xf bank_mask:0xf
	s_waitcnt lgkmcnt(0)
	v_add_f32_e32 v28, v28, v30
	s_nop 1
	v_mov_b32_dpp v30, v28 row_mirror row_mask:0xf bank_mask:0xf
	s_waitcnt lgkmcnt(0)
	v_add_f32_e32 v28, v28, v30
	s_waitcnt lgkmcnt(0)
	s_nop 0
	v_readlane_b32 s98, v28, 32
	v_readlane_b32 s100, v28, 48
	s_nop 1
	v_mov_b32_e32 v30, s100
	v_add_f32_e32 v30, s98, v30
	v_readlane_b32 s98, v28, 0
	v_readlane_b32 s100, v28, 16
	s_nop 1
	v_mov_b32_e32 v28, s100
	v_add_f32_e32 v28, s98, v28
	v_add_f32_e32 v28, v28, v30
	s_waitcnt lgkmcnt(0)
	v_fmamk_f32 v28, v28, 0x3a800000, v247
	v_mul_f32_e32 v30, 0x4b800000, v28
	v_cmp_gt_f32_e32 vcc, s35, v28
	s_nop 1
	v_cndmask_b32_e32 v28, v28, v30, vcc
	v_rsq_f32_e32 v28, v28
	s_nop 0
	v_mul_f32_e32 v30, 0x45800000, v28
	v_cndmask_b32_e32 v42, v28, v30, vcc
	v_pk_mul_f32 v[16:17], v[42:43], v[16:17] op_sel_hi:[0,1]
	v_pk_mul_f32 v[18:19], v[42:43], v[18:19] op_sel_hi:[0,1]
	v_pk_fma_f32 v[18:19], v[88:89], v[18:19], v[46:47]
	v_pk_fma_f32 v[16:17], v[86:87], v[16:17], v[44:45]
	s_and_b64 vcc, exec, s[6:7]
	v_lshl_add_u64 v[44:45], v[196:197], 2, s[0:1]
	s_cbranch_vccnz .LBB0_835
	global_store_dwordx4 v[44:45], v[16:19], off sc0 sc1
	s_cbranch_execnz .LBB0_584
.LBB0_583:
	v_cvt_pk_bf16_f32 v46, v16, v17
	v_cvt_pk_bf16_f32 v47, v18, v19
	global_store_dwordx2 v[198:199], v[46:47], off sc0 sc1
.LBB0_584:
	v_mov_b32_e32 v43, v42
	v_lshlrev_b32_e32 v46, 16, v204
	v_and_b32_e32 v47, 0xffff0000, v204
	v_lshlrev_b32_e32 v48, 16, v205
	v_and_b32_e32 v49, 0xffff0000, v205
	v_mov_b32_e32 v204, v21
	v_mov_b32_e32 v205, v23
	v_mov_b32_e32 v206, v42
	v_mov_b32_e32 v207, v42
	v_mov_b32_e32 v21, v22
	v_pk_mul_f32 v[204:205], v[206:207], v[204:205]
	v_pk_mul_f32 v[20:21], v[42:43], v[20:21]
	v_pk_fma_f32 v[22:23], v[92:93], v[204:205], v[48:49]
	s_and_b64 vcc, exec, s[6:7]
	v_pk_fma_f32 v[20:21], v[90:91], v[20:21], v[46:47]
	s_cbranch_vccnz .LBB0_836
	global_store_dwordx4 v[44:45], v[20:23], off offset:1024 sc0 sc1
	s_cbranch_execnz .LBB0_587
.LBB0_586:
	v_cvt_pk_bf16_f32 v46, v20, v21
	v_cvt_pk_bf16_f32 v47, v22, v23
	global_store_dwordx2 v[198:199], v[46:47], off offset:512 sc0 sc1
.LBB0_587:
	v_lshlrev_b32_e32 v46, 16, v202
	v_and_b32_e32 v47, 0xffff0000, v202
	v_lshlrev_b32_e32 v48, 16, v203
	v_and_b32_e32 v49, 0xffff0000, v203
	v_mov_b32_e32 v202, v42
	v_mov_b32_e32 v203, v42
	v_pk_mul_f32 v[24:25], v[42:43], v[24:25]
	v_pk_mul_f32 v[26:27], v[202:203], v[26:27]
	s_and_b64 vcc, exec, s[6:7]
	v_pk_fma_f32 v[26:27], v[36:37], v[26:27], v[48:49]
	v_pk_fma_f32 v[24:25], v[32:33], v[24:25], v[46:47]
	s_cbranch_vccnz .LBB0_837
	global_store_dwordx4 v[44:45], v[24:27], off offset:2048 sc0 sc1
	s_cbranch_execnz .LBB0_590
.LBB0_589:
	v_cvt_pk_bf16_f32 v46, v24, v25
	v_cvt_pk_bf16_f32 v47, v26, v27
	global_store_dwordx2 v[198:199], v[46:47], off offset:1024 sc0 sc1
.LBB0_590:
	v_lshlrev_b32_e32 v46, 16, v200
	v_and_b32_e32 v47, 0xffff0000, v200
	v_lshlrev_b32_e32 v48, 16, v201
	v_and_b32_e32 v49, 0xffff0000, v201
	v_mov_b32_e32 v200, v42
	v_mov_b32_e32 v201, v42
	v_mov_b32_e32 v28, v31
	v_pk_mul_f32 v[40:41], v[40:41], v[200:201]
	v_pk_mul_f32 v[28:29], v[28:29], v[42:43]
	v_pk_fma_f32 v[30:31], v[38:39], v[40:41], v[48:49]
	s_and_b64 vcc, exec, s[6:7]
	v_pk_fma_f32 v[28:29], v[34:35], v[28:29], v[46:47]
	s_cbranch_vccnz .LBB0_838
	global_store_dwordx4 v[44:45], v[28:31], off offset:3072 sc0 sc1
	s_cbranch_execnz .LBB0_593
.LBB0_592:
	v_cvt_pk_bf16_f32 v40, v28, v29
	v_cvt_pk_bf16_f32 v41, v30, v31
	global_store_dwordx2 v[198:199], v[40:41], off offset:1536 sc0 sc1
.LBB0_593:
	s_and_b64 vcc, exec, s[4:5]
	s_cbranch_vccnz .LBB0_595
	v_mul_f32_e32 v40, v17, v17
	v_mul_f32_e32 v41, v19, v19
	v_fmac_f32_e32 v40, v16, v16
	v_fmac_f32_e32 v41, v18, v18
	v_add_f32_e32 v40, v40, v41
	v_mul_f32_e32 v41, v21, v21
	v_mul_f32_e32 v42, v23, v23
	v_fmac_f32_e32 v41, v20, v20
	v_fmac_f32_e32 v42, v22, v22
	v_add_f32_e32 v41, v41, v42
	v_add_f32_e32 v40, v40, v41
	v_mul_f32_e32 v41, v25, v25
	v_mul_f32_e32 v42, v27, v27
	v_fmac_f32_e32 v41, v24, v24
	v_fmac_f32_e32 v42, v26, v26
	v_add_f32_e32 v41, v41, v42
	v_add_f32_e32 v40, v41, v40
	v_mul_f32_e32 v41, v29, v29
	v_mul_f32_e32 v42, v31, v31
	v_fmac_f32_e32 v41, v28, v28
	v_fmac_f32_e32 v42, v30, v30
	v_add_f32_e32 v41, v41, v42
	v_add_f32_e32 v40, v41, v40
	s_nop 1
	v_mov_b32_dpp v41, v40 quad_perm:[1,0,3,2] row_mask:0xf bank_mask:0xf
	s_waitcnt lgkmcnt(0)
	v_add_f32_e32 v40, v40, v41
	s_nop 1
	v_mov_b32_dpp v41, v40 quad_perm:[2,3,0,1] row_mask:0xf bank_mask:0xf
	s_waitcnt lgkmcnt(0)
	v_add_f32_e32 v40, v40, v41
	s_nop 1
	v_mov_b32_dpp v41, v40 row_half_mirror row_mask:0xf bank_mask:0xf
	s_waitcnt lgkmcnt(0)
	v_add_f32_e32 v40, v40, v41
	s_nop 1
	v_mov_b32_dpp v41, v40 row_mirror row_mask:0xf bank_mask:0xf
	s_waitcnt lgkmcnt(0)
	v_add_f32_e32 v40, v40, v41
	s_waitcnt lgkmcnt(0)
	s_nop 0
	v_readlane_b32 s98, v40, 32
	v_readlane_b32 s100, v40, 48
	s_nop 1
	v_mov_b32_e32 v41, s100
	v_add_f32_e32 v41, s98, v41
	v_readlane_b32 s98, v40, 0
	v_readlane_b32 s100, v40, 16
	s_nop 1
	v_mov_b32_e32 v40, s100
	v_add_f32_e32 v40, s98, v40
	v_add_f32_e32 v40, v40, v41
	s_waitcnt lgkmcnt(0)
	v_fmamk_f32 v40, v40, 0x3a800000, v247
	v_mul_f32_e32 v41, 0x4b800000, v40
	v_cmp_gt_f32_e32 vcc, s35, v40
	s_nop 1
	v_cndmask_b32_e32 v40, v40, v41, vcc
	v_rsq_f32_e32 v42, v40
	v_lshl_add_u64 v[40:41], v[196:197], 1, s[42:43]
	v_mul_f32_e32 v43, 0x45800000, v42
	v_cndmask_b32_e32 v42, v42, v43, vcc
	v_pk_mul_f32 v[16:17], v[16:17], v[42:43] op_sel_hi:[1,0]
	v_pk_mul_f32 v[18:19], v[18:19], v[42:43] op_sel_hi:[1,0]
	v_pk_mul_f32 v[20:21], v[20:21], v[42:43] op_sel_hi:[1,0]
	v_pk_mul_f32 v[22:23], v[22:23], v[42:43] op_sel_hi:[1,0]
	v_pk_fma_f32 v[18:19], v[54:55], v[18:19], v[2:3]
	v_pk_fma_f32 v[16:17], v[52:53], v[16:17], v[0:1]
	v_pk_fma_f32 v[22:23], v[56:57], v[22:23], v[6:7]
	v_pk_fma_f32 v[20:21], v[50:51], v[20:21], v[4:5]
	v_cvt_pk_bf16_f32 v16, v16, v17
	v_cvt_pk_bf16_f32 v17, v18, v19
	v_cvt_pk_bf16_f32 v18, v20, v21
	v_cvt_pk_bf16_f32 v19, v22, v23
	global_store_dwordx2 v[40:41], v[16:17], off sc0 sc1
	global_store_dwordx2 v[40:41], v[18:19], off offset:512 sc0 sc1
	v_pk_mul_f32 v[16:17], v[24:25], v[42:43] op_sel_hi:[1,0]
	v_pk_mul_f32 v[18:19], v[26:27], v[42:43] op_sel_hi:[1,0]
	v_pk_fma_f32 v[16:17], v[60:61], v[16:17], v[8:9]
	v_pk_fma_f32 v[18:19], v[62:63], v[18:19], v[10:11]
	v_cvt_pk_bf16_f32 v16, v16, v17
	v_cvt_pk_bf16_f32 v17, v18, v19
	global_store_dwordx2 v[40:41], v[16:17], off offset:1024 sc0 sc1
	v_pk_mul_f32 v[16:17], v[28:29], v[42:43] op_sel_hi:[1,0]
	v_pk_mul_f32 v[18:19], v[30:31], v[42:43] op_sel_hi:[1,0]
	v_pk_fma_f32 v[16:17], v[58:59], v[16:17], v[12:13]
	v_pk_fma_f32 v[18:19], v[64:65], v[18:19], v[14:15]
	v_cvt_pk_bf16_f32 v16, v16, v17
	v_cvt_pk_bf16_f32 v17, v18, v19
	global_store_dwordx2 v[40:41], v[16:17], off offset:1536 sc0 sc1
.LBB0_595:
	v_and_b32_e32 v17, 0xffff0000, v194
	v_and_b32_e32 v19, 0xffff0000, v195
	v_lshlrev_b32_e32 v16, 16, v194
	v_lshlrev_b32_e32 v18, 16, v195
	v_mul_f32_e32 v20, v19, v19
	v_and_b32_e32 v23, 0xffff0000, v193
	v_and_b32_e32 v22, 0xffff0000, v192
	v_and_b32_e32 v29, 0xffff0000, v188
	v_mul_f32_e32 v28, v17, v17
	v_pk_fma_f32 v[42:43], v[18:19], v[18:19], v[20:21] op_sel_hi:[1,1,0]
	v_lshlrev_b32_e32 v21, 16, v193
	v_lshlrev_b32_e32 v20, 16, v192
	v_pk_mul_f32 v[24:25], v[22:23], v[22:23]
	v_lshlrev_b32_e32 v31, 16, v188
	v_pk_fma_f32 v[46:47], v[16:17], v[16:17], v[28:29] op_sel_hi:[1,1,0]
	v_pk_fma_f32 v[44:45], v[20:21], v[20:21], v[24:25]
	v_mov_b32_e32 v30, v46
	v_mov_b32_e32 v48, v42
	v_mov_b32_e32 v49, v31
	v_and_b32_e32 v25, 0xffff0000, v190
	v_mul_f32_e32 v188, v29, v29
	v_pk_add_f32 v[42:43], v[46:47], v[42:43]
	v_pk_mul_f32 v[46:47], v[30:31], v[48:49]
	v_pk_add_f32 v[44:45], v[44:45], v[44:45] op_sel:[0,1] op_sel_hi:[1,0]
	v_lshlrev_b32_e32 v24, 16, v190
	v_and_b32_e32 v27, 0xffff0000, v191
	v_mov_b32_e32 v43, v47
	v_mov_b32_e32 v45, v188
	v_mul_f32_e32 v28, v25, v25
	v_lshlrev_b32_e32 v26, 16, v191
	v_lshlrev_b32_e32 v40, 16, v189
	v_and_b32_e32 v41, 0xffff0000, v189
	v_pk_add_f32 v[42:43], v[42:43], v[44:45]
	v_pk_fma_f32 v[44:45], v[24:25], v[24:25], v[28:29] op_sel_hi:[1,1,0]
	v_mul_f32_e32 v28, v27, v27
	v_mul_f32_e32 v189, v40, v40
	v_mul_f32_e32 v190, v41, v41
	v_pk_fma_f32 v[46:47], v[26:27], v[26:27], v[28:29] op_sel_hi:[1,1,0]
	v_mov_b32_e32 v45, v189
	v_mov_b32_e32 v47, v190
	v_pk_add_f32 v[44:45], v[44:45], v[46:47]
	v_lshlrev_b32_e32 v46, 16, v187
	v_pk_add_f32 v[42:43], v[42:43], v[44:45]
	v_lshlrev_b32_e32 v44, 16, v186
	v_add_f32_e32 v28, v42, v43
	s_nop 1
	v_mov_b32_dpp v30, v28 quad_perm:[1,0,3,2] row_mask:0xf bank_mask:0xf
	v_and_b32_e32 v45, 0xffff0000, v186
	v_and_b32_e32 v47, 0xffff0000, v187
	s_waitcnt lgkmcnt(0)
	v_add_f32_e32 v28, v28, v30
	s_nop 1
	v_mov_b32_dpp v30, v28 quad_perm:[2,3,0,1] row_mask:0xf bank_mask:0xf
	s_waitcnt lgkmcnt(0)
	v_add_f32_e32 v28, v28, v30
	s_nop 1
	v_mov_b32_dpp v30, v28 row_half_mirror row_mask:0xf bank_mask:0xf
	s_waitcnt lgkmcnt(0)
	v_add_f32_e32 v28, v28, v30
	s_nop 1
	v_mov_b32_dpp v30, v28 row_mirror row_mask:0xf bank_mask:0xf
	s_waitcnt lgkmcnt(0)
	v_add_f32_e32 v28, v28, v30
	s_waitcnt lgkmcnt(0)
	s_nop 0
	v_readlane_b32 s98, v28, 32
	v_readlane_b32 s100, v28, 48
	s_nop 1
	v_mov_b32_e32 v30, s100
	v_add_f32_e32 v30, s98, v30
	v_readlane_b32 s98, v28, 0
	v_readlane_b32 s100, v28, 16
	s_nop 1
	v_mov_b32_e32 v28, s100
	v_add_f32_e32 v28, s98, v28
	v_add_f32_e32 v28, v28, v30
	s_waitcnt lgkmcnt(0)
	v_fmamk_f32 v28, v28, 0x3a800000, v247
	v_mul_f32_e32 v30, 0x4b800000, v28
	v_cmp_gt_f32_e32 vcc, s35, v28
	s_nop 1
	v_cndmask_b32_e32 v28, v28, v30, vcc
	v_rsq_f32_e32 v28, v28
	s_nop 0
	v_mul_f32_e32 v30, 0x45800000, v28
	v_cndmask_b32_e32 v42, v28, v30, vcc
	v_pk_mul_f32 v[16:17], v[42:43], v[16:17] op_sel_hi:[0,1]
	v_pk_mul_f32 v[18:19], v[42:43], v[18:19] op_sel_hi:[0,1]
	v_pk_fma_f32 v[18:19], v[88:89], v[18:19], v[46:47]
	v_pk_fma_f32 v[16:17], v[86:87], v[16:17], v[44:45]
	s_and_b64 vcc, exec, s[6:7]
	v_lshl_add_u64 v[44:45], v[176:177], 2, s[0:1]
	s_cbranch_vccnz .LBB0_839
	global_store_dwordx4 v[44:45], v[16:19], off sc0 sc1
	s_cbranch_execnz .LBB0_598
.LBB0_597:
	v_cvt_pk_bf16_f32 v46, v16, v17
	v_cvt_pk_bf16_f32 v47, v18, v19
	global_store_dwordx2 v[178:179], v[46:47], off sc0 sc1
.LBB0_598:
	v_mov_b32_e32 v43, v42
	v_lshlrev_b32_e32 v46, 16, v184
	v_and_b32_e32 v47, 0xffff0000, v184
	v_lshlrev_b32_e32 v48, 16, v185
	v_and_b32_e32 v49, 0xffff0000, v185
	v_mov_b32_e32 v184, v21
	v_mov_b32_e32 v185, v23
	v_mov_b32_e32 v186, v42
	v_mov_b32_e32 v187, v42
	v_mov_b32_e32 v21, v22
	v_pk_mul_f32 v[184:185], v[186:187], v[184:185]
	v_pk_mul_f32 v[20:21], v[42:43], v[20:21]
	v_pk_fma_f32 v[22:23], v[92:93], v[184:185], v[48:49]
	s_and_b64 vcc, exec, s[6:7]
	v_pk_fma_f32 v[20:21], v[90:91], v[20:21], v[46:47]
	s_cbranch_vccnz .LBB0_840
	global_store_dwordx4 v[44:45], v[20:23], off offset:1024 sc0 sc1
	s_cbranch_execnz .LBB0_601
.LBB0_600:
	v_cvt_pk_bf16_f32 v46, v20, v21
	v_cvt_pk_bf16_f32 v47, v22, v23
	global_store_dwordx2 v[178:179], v[46:47], off offset:512 sc0 sc1
.LBB0_601:
	v_lshlrev_b32_e32 v46, 16, v182
	v_and_b32_e32 v47, 0xffff0000, v182
	v_lshlrev_b32_e32 v48, 16, v183
	v_and_b32_e32 v49, 0xffff0000, v183
	v_mov_b32_e32 v182, v42
	v_mov_b32_e32 v183, v42
	v_pk_mul_f32 v[24:25], v[42:43], v[24:25]
	v_pk_mul_f32 v[26:27], v[182:183], v[26:27]
	s_and_b64 vcc, exec, s[6:7]
	v_pk_fma_f32 v[26:27], v[36:37], v[26:27], v[48:49]
	v_pk_fma_f32 v[24:25], v[32:33], v[24:25], v[46:47]
	s_cbranch_vccnz .LBB0_841
	global_store_dwordx4 v[44:45], v[24:27], off offset:2048 sc0 sc1
	s_cbranch_execnz .LBB0_604
.LBB0_603:
	v_cvt_pk_bf16_f32 v46, v24, v25
	v_cvt_pk_bf16_f32 v47, v26, v27
	global_store_dwordx2 v[178:179], v[46:47], off offset:1024 sc0 sc1
.LBB0_604:
	v_lshlrev_b32_e32 v46, 16, v180
	v_and_b32_e32 v47, 0xffff0000, v180
	v_lshlrev_b32_e32 v48, 16, v181
	v_and_b32_e32 v49, 0xffff0000, v181
	v_mov_b32_e32 v180, v42
	v_mov_b32_e32 v181, v42
	v_mov_b32_e32 v28, v31
	v_pk_mul_f32 v[40:41], v[40:41], v[180:181]
	v_pk_mul_f32 v[28:29], v[28:29], v[42:43]
	v_pk_fma_f32 v[30:31], v[38:39], v[40:41], v[48:49]
	s_and_b64 vcc, exec, s[6:7]
	v_pk_fma_f32 v[28:29], v[34:35], v[28:29], v[46:47]
	s_cbranch_vccnz .LBB0_842
	global_store_dwordx4 v[44:45], v[28:31], off offset:3072 sc0 sc1
	s_cbranch_execnz .LBB0_607
.LBB0_606:
	v_cvt_pk_bf16_f32 v40, v28, v29
	v_cvt_pk_bf16_f32 v41, v30, v31
	global_store_dwordx2 v[178:179], v[40:41], off offset:1536 sc0 sc1
.LBB0_607:
	s_and_b64 vcc, exec, s[4:5]
	s_cbranch_vccnz .LBB0_609
	v_mul_f32_e32 v40, v17, v17
	v_mul_f32_e32 v41, v19, v19
	v_fmac_f32_e32 v40, v16, v16
	v_fmac_f32_e32 v41, v18, v18
	v_add_f32_e32 v40, v40, v41
	v_mul_f32_e32 v41, v21, v21
	v_mul_f32_e32 v42, v23, v23
	v_fmac_f32_e32 v41, v20, v20
	v_fmac_f32_e32 v42, v22, v22
	v_add_f32_e32 v41, v41, v42
	v_add_f32_e32 v40, v40, v41
	v_mul_f32_e32 v41, v25, v25
	v_mul_f32_e32 v42, v27, v27
	v_fmac_f32_e32 v41, v24, v24
	v_fmac_f32_e32 v42, v26, v26
	v_add_f32_e32 v41, v41, v42
	v_add_f32_e32 v40, v41, v40
	v_mul_f32_e32 v41, v29, v29
	v_mul_f32_e32 v42, v31, v31
	v_fmac_f32_e32 v41, v28, v28
	v_fmac_f32_e32 v42, v30, v30
	v_add_f32_e32 v41, v41, v42
	v_add_f32_e32 v40, v41, v40
	s_nop 1
	v_mov_b32_dpp v41, v40 quad_perm:[1,0,3,2] row_mask:0xf bank_mask:0xf
	s_waitcnt lgkmcnt(0)
	v_add_f32_e32 v40, v40, v41
	s_nop 1
	v_mov_b32_dpp v41, v40 quad_perm:[2,3,0,1] row_mask:0xf bank_mask:0xf
	s_waitcnt lgkmcnt(0)
	v_add_f32_e32 v40, v40, v41
	s_nop 1
	v_mov_b32_dpp v41, v40 row_half_mirror row_mask:0xf bank_mask:0xf
	s_waitcnt lgkmcnt(0)
	v_add_f32_e32 v40, v40, v41
	s_nop 1
	v_mov_b32_dpp v41, v40 row_mirror row_mask:0xf bank_mask:0xf
	s_waitcnt lgkmcnt(0)
	v_add_f32_e32 v40, v40, v41
	s_waitcnt lgkmcnt(0)
	s_nop 0
	v_readlane_b32 s98, v40, 32
	v_readlane_b32 s100, v40, 48
	s_nop 1
	v_mov_b32_e32 v41, s100
	v_add_f32_e32 v41, s98, v41
	v_readlane_b32 s98, v40, 0
	v_readlane_b32 s100, v40, 16
	s_nop 1
	v_mov_b32_e32 v40, s100
	v_add_f32_e32 v40, s98, v40
	v_add_f32_e32 v40, v40, v41
	s_waitcnt lgkmcnt(0)
	v_fmamk_f32 v40, v40, 0x3a800000, v247
	v_mul_f32_e32 v41, 0x4b800000, v40
	v_cmp_gt_f32_e32 vcc, s35, v40
	s_nop 1
	v_cndmask_b32_e32 v40, v40, v41, vcc
	v_rsq_f32_e32 v42, v40
	v_lshl_add_u64 v[40:41], v[176:177], 1, s[42:43]
	v_mul_f32_e32 v43, 0x45800000, v42
	v_cndmask_b32_e32 v42, v42, v43, vcc
	v_pk_mul_f32 v[16:17], v[16:17], v[42:43] op_sel_hi:[1,0]
	v_pk_mul_f32 v[18:19], v[18:19], v[42:43] op_sel_hi:[1,0]
	v_pk_mul_f32 v[20:21], v[20:21], v[42:43] op_sel_hi:[1,0]
	v_pk_mul_f32 v[22:23], v[22:23], v[42:43] op_sel_hi:[1,0]
	v_pk_fma_f32 v[18:19], v[54:55], v[18:19], v[2:3]
	v_pk_fma_f32 v[16:17], v[52:53], v[16:17], v[0:1]
	v_pk_fma_f32 v[22:23], v[56:57], v[22:23], v[6:7]
	v_pk_fma_f32 v[20:21], v[50:51], v[20:21], v[4:5]
	v_cvt_pk_bf16_f32 v16, v16, v17
	v_cvt_pk_bf16_f32 v17, v18, v19
	v_cvt_pk_bf16_f32 v18, v20, v21
	v_cvt_pk_bf16_f32 v19, v22, v23
	global_store_dwordx2 v[40:41], v[16:17], off sc0 sc1
	global_store_dwordx2 v[40:41], v[18:19], off offset:512 sc0 sc1
	v_pk_mul_f32 v[16:17], v[24:25], v[42:43] op_sel_hi:[1,0]
	v_pk_mul_f32 v[18:19], v[26:27], v[42:43] op_sel_hi:[1,0]
	v_pk_fma_f32 v[16:17], v[60:61], v[16:17], v[8:9]
	v_pk_fma_f32 v[18:19], v[62:63], v[18:19], v[10:11]
	v_cvt_pk_bf16_f32 v16, v16, v17
	v_cvt_pk_bf16_f32 v17, v18, v19
	global_store_dwordx2 v[40:41], v[16:17], off offset:1024 sc0 sc1
	v_pk_mul_f32 v[16:17], v[28:29], v[42:43] op_sel_hi:[1,0]
	v_pk_mul_f32 v[18:19], v[30:31], v[42:43] op_sel_hi:[1,0]
	v_pk_fma_f32 v[16:17], v[58:59], v[16:17], v[12:13]
	v_pk_fma_f32 v[18:19], v[64:65], v[18:19], v[14:15]
	v_cvt_pk_bf16_f32 v16, v16, v17
	v_cvt_pk_bf16_f32 v17, v18, v19
	global_store_dwordx2 v[40:41], v[16:17], off offset:1536 sc0 sc1
.LBB0_609:
	v_and_b32_e32 v17, 0xffff0000, v174
	v_and_b32_e32 v19, 0xffff0000, v175
	v_lshlrev_b32_e32 v16, 16, v174
	v_lshlrev_b32_e32 v18, 16, v175
	v_mul_f32_e32 v20, v19, v19
	v_and_b32_e32 v23, 0xffff0000, v173
	v_and_b32_e32 v22, 0xffff0000, v172
	v_and_b32_e32 v29, 0xffff0000, v168
	v_mul_f32_e32 v28, v17, v17
	v_pk_fma_f32 v[42:43], v[18:19], v[18:19], v[20:21] op_sel_hi:[1,1,0]
	v_lshlrev_b32_e32 v21, 16, v173
	v_lshlrev_b32_e32 v20, 16, v172
	v_pk_mul_f32 v[24:25], v[22:23], v[22:23]
	v_lshlrev_b32_e32 v31, 16, v168
	v_pk_fma_f32 v[46:47], v[16:17], v[16:17], v[28:29] op_sel_hi:[1,1,0]
	v_pk_fma_f32 v[44:45], v[20:21], v[20:21], v[24:25]
	v_mov_b32_e32 v30, v46
	v_mov_b32_e32 v48, v42
	v_mov_b32_e32 v49, v31
	v_and_b32_e32 v25, 0xffff0000, v170
	v_mul_f32_e32 v168, v29, v29
	v_pk_add_f32 v[42:43], v[46:47], v[42:43]
	v_pk_mul_f32 v[46:47], v[30:31], v[48:49]
	v_pk_add_f32 v[44:45], v[44:45], v[44:45] op_sel:[0,1] op_sel_hi:[1,0]
	v_lshlrev_b32_e32 v24, 16, v170
	v_and_b32_e32 v27, 0xffff0000, v171
	v_mov_b32_e32 v43, v47
	v_mov_b32_e32 v45, v168
	v_mul_f32_e32 v28, v25, v25
	v_lshlrev_b32_e32 v26, 16, v171
	v_lshlrev_b32_e32 v40, 16, v169
	v_and_b32_e32 v41, 0xffff0000, v169
	v_pk_add_f32 v[42:43], v[42:43], v[44:45]
	v_pk_fma_f32 v[44:45], v[24:25], v[24:25], v[28:29] op_sel_hi:[1,1,0]
	v_mul_f32_e32 v28, v27, v27
	v_mul_f32_e32 v169, v40, v40
	v_mul_f32_e32 v170, v41, v41
	v_pk_fma_f32 v[46:47], v[26:27], v[26:27], v[28:29] op_sel_hi:[1,1,0]
	v_mov_b32_e32 v45, v169
	v_mov_b32_e32 v47, v170
	v_pk_add_f32 v[44:45], v[44:45], v[46:47]
	v_lshlrev_b32_e32 v46, 16, v167
	v_pk_add_f32 v[42:43], v[42:43], v[44:45]
	v_lshlrev_b32_e32 v44, 16, v166
	v_add_f32_e32 v28, v42, v43
	s_nop 1
	v_mov_b32_dpp v30, v28 quad_perm:[1,0,3,2] row_mask:0xf bank_mask:0xf
	v_and_b32_e32 v45, 0xffff0000, v166
	v_and_b32_e32 v47, 0xffff0000, v167
	s_waitcnt lgkmcnt(0)
	v_add_f32_e32 v28, v28, v30
	s_nop 1
	v_mov_b32_dpp v30, v28 quad_perm:[2,3,0,1] row_mask:0xf bank_mask:0xf
	s_waitcnt lgkmcnt(0)
	v_add_f32_e32 v28, v28, v30
	s_nop 1
	v_mov_b32_dpp v30, v28 row_half_mirror row_mask:0xf bank_mask:0xf
	s_waitcnt lgkmcnt(0)
	v_add_f32_e32 v28, v28, v30
	s_nop 1
	v_mov_b32_dpp v30, v28 row_mirror row_mask:0xf bank_mask:0xf
	s_waitcnt lgkmcnt(0)
	v_add_f32_e32 v28, v28, v30
	s_waitcnt lgkmcnt(0)
	s_nop 0
	v_readlane_b32 s98, v28, 32
	v_readlane_b32 s100, v28, 48
	s_nop 1
	v_mov_b32_e32 v30, s100
	v_add_f32_e32 v30, s98, v30
	v_readlane_b32 s98, v28, 0
	v_readlane_b32 s100, v28, 16
	s_nop 1
	v_mov_b32_e32 v28, s100
	v_add_f32_e32 v28, s98, v28
	v_add_f32_e32 v28, v28, v30
	s_waitcnt lgkmcnt(0)
	v_fmamk_f32 v28, v28, 0x3a800000, v247
	v_mul_f32_e32 v30, 0x4b800000, v28
	v_cmp_gt_f32_e32 vcc, s35, v28
	s_nop 1
	v_cndmask_b32_e32 v28, v28, v30, vcc
	v_rsq_f32_e32 v28, v28
	s_nop 0
	v_mul_f32_e32 v30, 0x45800000, v28
	v_cndmask_b32_e32 v42, v28, v30, vcc
	v_pk_mul_f32 v[16:17], v[42:43], v[16:17] op_sel_hi:[0,1]
	v_pk_mul_f32 v[18:19], v[42:43], v[18:19] op_sel_hi:[0,1]
	v_pk_fma_f32 v[18:19], v[88:89], v[18:19], v[46:47]
	v_pk_fma_f32 v[16:17], v[86:87], v[16:17], v[44:45]
	s_and_b64 vcc, exec, s[6:7]
	v_lshl_add_u64 v[44:45], v[156:157], 2, s[0:1]
	s_cbranch_vccnz .LBB0_843
	global_store_dwordx4 v[44:45], v[16:19], off sc0 sc1
	s_cbranch_execnz .LBB0_612
.LBB0_611:
	v_cvt_pk_bf16_f32 v46, v16, v17
	v_cvt_pk_bf16_f32 v47, v18, v19
	global_store_dwordx2 v[158:159], v[46:47], off sc0 sc1
.LBB0_612:
	v_mov_b32_e32 v43, v42
	v_lshlrev_b32_e32 v46, 16, v164
	v_and_b32_e32 v47, 0xffff0000, v164
	v_lshlrev_b32_e32 v48, 16, v165
	v_and_b32_e32 v49, 0xffff0000, v165
	v_mov_b32_e32 v164, v21
	v_mov_b32_e32 v165, v23
	v_mov_b32_e32 v166, v42
	v_mov_b32_e32 v167, v42
	v_mov_b32_e32 v21, v22
	v_pk_mul_f32 v[164:165], v[166:167], v[164:165]
	v_pk_mul_f32 v[20:21], v[42:43], v[20:21]
	v_pk_fma_f32 v[22:23], v[92:93], v[164:165], v[48:49]
	s_and_b64 vcc, exec, s[6:7]
	v_pk_fma_f32 v[20:21], v[90:91], v[20:21], v[46:47]
	s_cbranch_vccnz .LBB0_844
	global_store_dwordx4 v[44:45], v[20:23], off offset:1024 sc0 sc1
	s_cbranch_execnz .LBB0_615
.LBB0_614:
	v_cvt_pk_bf16_f32 v46, v20, v21
	v_cvt_pk_bf16_f32 v47, v22, v23
	global_store_dwordx2 v[158:159], v[46:47], off offset:512 sc0 sc1
.LBB0_615:
	v_lshlrev_b32_e32 v46, 16, v162
	v_and_b32_e32 v47, 0xffff0000, v162
	v_lshlrev_b32_e32 v48, 16, v163
	v_and_b32_e32 v49, 0xffff0000, v163
	v_mov_b32_e32 v162, v42
	v_mov_b32_e32 v163, v42
	v_pk_mul_f32 v[24:25], v[42:43], v[24:25]
	v_pk_mul_f32 v[26:27], v[162:163], v[26:27]
	s_and_b64 vcc, exec, s[6:7]
	v_pk_fma_f32 v[26:27], v[36:37], v[26:27], v[48:49]
	v_pk_fma_f32 v[24:25], v[32:33], v[24:25], v[46:47]
	s_cbranch_vccnz .LBB0_845
	global_store_dwordx4 v[44:45], v[24:27], off offset:2048 sc0 sc1
	s_cbranch_execnz .LBB0_618
.LBB0_617:
	v_cvt_pk_bf16_f32 v46, v24, v25
	v_cvt_pk_bf16_f32 v47, v26, v27
	global_store_dwordx2 v[158:159], v[46:47], off offset:1024 sc0 sc1
.LBB0_618:
	v_lshlrev_b32_e32 v46, 16, v160
	v_and_b32_e32 v47, 0xffff0000, v160
	v_lshlrev_b32_e32 v48, 16, v161
	v_and_b32_e32 v49, 0xffff0000, v161
	v_mov_b32_e32 v160, v42
	v_mov_b32_e32 v161, v42
	v_mov_b32_e32 v28, v31
	v_pk_mul_f32 v[40:41], v[40:41], v[160:161]
	v_pk_mul_f32 v[28:29], v[28:29], v[42:43]
	v_pk_fma_f32 v[30:31], v[38:39], v[40:41], v[48:49]
	s_and_b64 vcc, exec, s[6:7]
	v_pk_fma_f32 v[28:29], v[34:35], v[28:29], v[46:47]
	s_cbranch_vccnz .LBB0_846
	global_store_dwordx4 v[44:45], v[28:31], off offset:3072 sc0 sc1
	s_cbranch_execnz .LBB0_621
.LBB0_620:
	v_cvt_pk_bf16_f32 v40, v28, v29
	v_cvt_pk_bf16_f32 v41, v30, v31
	global_store_dwordx2 v[158:159], v[40:41], off offset:1536 sc0 sc1
.LBB0_621:
	s_and_b64 vcc, exec, s[4:5]
	s_cbranch_vccnz .LBB0_623
	v_mul_f32_e32 v40, v17, v17
	v_mul_f32_e32 v41, v19, v19
	v_fmac_f32_e32 v40, v16, v16
	v_fmac_f32_e32 v41, v18, v18
	v_add_f32_e32 v40, v40, v41
	v_mul_f32_e32 v41, v21, v21
	v_mul_f32_e32 v42, v23, v23
	v_fmac_f32_e32 v41, v20, v20
	v_fmac_f32_e32 v42, v22, v22
	v_add_f32_e32 v41, v41, v42
	v_add_f32_e32 v40, v40, v41
	v_mul_f32_e32 v41, v25, v25
	v_mul_f32_e32 v42, v27, v27
	v_fmac_f32_e32 v41, v24, v24
	v_fmac_f32_e32 v42, v26, v26
	v_add_f32_e32 v41, v41, v42
	v_add_f32_e32 v40, v41, v40
	v_mul_f32_e32 v41, v29, v29
	v_mul_f32_e32 v42, v31, v31
	v_fmac_f32_e32 v41, v28, v28
	v_fmac_f32_e32 v42, v30, v30
	v_add_f32_e32 v41, v41, v42
	v_add_f32_e32 v40, v41, v40
	s_nop 1
	v_mov_b32_dpp v41, v40 quad_perm:[1,0,3,2] row_mask:0xf bank_mask:0xf
	s_waitcnt lgkmcnt(0)
	v_add_f32_e32 v40, v40, v41
	s_nop 1
	v_mov_b32_dpp v41, v40 quad_perm:[2,3,0,1] row_mask:0xf bank_mask:0xf
	s_waitcnt lgkmcnt(0)
	v_add_f32_e32 v40, v40, v41
	s_nop 1
	v_mov_b32_dpp v41, v40 row_half_mirror row_mask:0xf bank_mask:0xf
	s_waitcnt lgkmcnt(0)
	v_add_f32_e32 v40, v40, v41
	s_nop 1
	v_mov_b32_dpp v41, v40 row_mirror row_mask:0xf bank_mask:0xf
	s_waitcnt lgkmcnt(0)
	v_add_f32_e32 v40, v40, v41
	s_waitcnt lgkmcnt(0)
	s_nop 0
	v_readlane_b32 s98, v40, 32
	v_readlane_b32 s100, v40, 48
	s_nop 1
	v_mov_b32_e32 v41, s100
	v_add_f32_e32 v41, s98, v41
	v_readlane_b32 s98, v40, 0
	v_readlane_b32 s100, v40, 16
	s_nop 1
	v_mov_b32_e32 v40, s100
	v_add_f32_e32 v40, s98, v40
	v_add_f32_e32 v40, v40, v41
	s_waitcnt lgkmcnt(0)
	v_fmamk_f32 v40, v40, 0x3a800000, v247
	v_mul_f32_e32 v41, 0x4b800000, v40
	v_cmp_gt_f32_e32 vcc, s35, v40
	s_nop 1
	v_cndmask_b32_e32 v40, v40, v41, vcc
	v_rsq_f32_e32 v42, v40
	v_lshl_add_u64 v[40:41], v[156:157], 1, s[42:43]
	v_mul_f32_e32 v43, 0x45800000, v42
	v_cndmask_b32_e32 v42, v42, v43, vcc
	v_pk_mul_f32 v[16:17], v[16:17], v[42:43] op_sel_hi:[1,0]
	v_pk_mul_f32 v[18:19], v[18:19], v[42:43] op_sel_hi:[1,0]
	v_pk_mul_f32 v[20:21], v[20:21], v[42:43] op_sel_hi:[1,0]
	v_pk_mul_f32 v[22:23], v[22:23], v[42:43] op_sel_hi:[1,0]
	v_pk_fma_f32 v[18:19], v[54:55], v[18:19], v[2:3]
	v_pk_fma_f32 v[16:17], v[52:53], v[16:17], v[0:1]
	v_pk_fma_f32 v[22:23], v[56:57], v[22:23], v[6:7]
	v_pk_fma_f32 v[20:21], v[50:51], v[20:21], v[4:5]
	v_cvt_pk_bf16_f32 v16, v16, v17
	v_cvt_pk_bf16_f32 v17, v18, v19
	v_cvt_pk_bf16_f32 v18, v20, v21
	v_cvt_pk_bf16_f32 v19, v22, v23
	global_store_dwordx2 v[40:41], v[16:17], off sc0 sc1
	global_store_dwordx2 v[40:41], v[18:19], off offset:512 sc0 sc1
	v_pk_mul_f32 v[16:17], v[24:25], v[42:43] op_sel_hi:[1,0]
	v_pk_mul_f32 v[18:19], v[26:27], v[42:43] op_sel_hi:[1,0]
	v_pk_fma_f32 v[16:17], v[60:61], v[16:17], v[8:9]
	v_pk_fma_f32 v[18:19], v[62:63], v[18:19], v[10:11]
	v_cvt_pk_bf16_f32 v16, v16, v17
	v_cvt_pk_bf16_f32 v17, v18, v19
	global_store_dwordx2 v[40:41], v[16:17], off offset:1024 sc0 sc1
	v_pk_mul_f32 v[16:17], v[28:29], v[42:43] op_sel_hi:[1,0]
	v_pk_mul_f32 v[18:19], v[30:31], v[42:43] op_sel_hi:[1,0]
	v_pk_fma_f32 v[16:17], v[58:59], v[16:17], v[12:13]
	v_pk_fma_f32 v[18:19], v[64:65], v[18:19], v[14:15]
	v_cvt_pk_bf16_f32 v16, v16, v17
	v_cvt_pk_bf16_f32 v17, v18, v19
	global_store_dwordx2 v[40:41], v[16:17], off offset:1536 sc0 sc1
.LBB0_623:
	v_and_b32_e32 v17, 0xffff0000, v154
	v_and_b32_e32 v19, 0xffff0000, v155
	v_lshlrev_b32_e32 v16, 16, v154
	v_lshlrev_b32_e32 v18, 16, v155
	v_mul_f32_e32 v20, v19, v19
	v_and_b32_e32 v23, 0xffff0000, v153
	v_and_b32_e32 v22, 0xffff0000, v152
	v_and_b32_e32 v29, 0xffff0000, v148
	v_mul_f32_e32 v28, v17, v17
	v_pk_fma_f32 v[42:43], v[18:19], v[18:19], v[20:21] op_sel_hi:[1,1,0]
	v_lshlrev_b32_e32 v21, 16, v153
	v_lshlrev_b32_e32 v20, 16, v152
	v_pk_mul_f32 v[24:25], v[22:23], v[22:23]
	v_lshlrev_b32_e32 v31, 16, v148
	v_pk_fma_f32 v[46:47], v[16:17], v[16:17], v[28:29] op_sel_hi:[1,1,0]
	v_pk_fma_f32 v[44:45], v[20:21], v[20:21], v[24:25]
	v_mov_b32_e32 v30, v46
	v_mov_b32_e32 v48, v42
	v_mov_b32_e32 v49, v31
	v_and_b32_e32 v25, 0xffff0000, v150
	v_mul_f32_e32 v148, v29, v29
	v_pk_add_f32 v[42:43], v[46:47], v[42:43]
	v_pk_mul_f32 v[46:47], v[30:31], v[48:49]
	v_pk_add_f32 v[44:45], v[44:45], v[44:45] op_sel:[0,1] op_sel_hi:[1,0]
	v_lshlrev_b32_e32 v24, 16, v150
	v_and_b32_e32 v27, 0xffff0000, v151
	v_mov_b32_e32 v43, v47
	v_mov_b32_e32 v45, v148
	v_mul_f32_e32 v28, v25, v25
	v_lshlrev_b32_e32 v26, 16, v151
	v_lshlrev_b32_e32 v40, 16, v149
	v_and_b32_e32 v41, 0xffff0000, v149
	v_pk_add_f32 v[42:43], v[42:43], v[44:45]
	v_pk_fma_f32 v[44:45], v[24:25], v[24:25], v[28:29] op_sel_hi:[1,1,0]
	v_mul_f32_e32 v28, v27, v27
	v_mul_f32_e32 v149, v40, v40
	v_mul_f32_e32 v150, v41, v41
	v_pk_fma_f32 v[46:47], v[26:27], v[26:27], v[28:29] op_sel_hi:[1,1,0]
	v_mov_b32_e32 v45, v149
	v_mov_b32_e32 v47, v150
	v_pk_add_f32 v[44:45], v[44:45], v[46:47]
	v_lshlrev_b32_e32 v46, 16, v147
	v_pk_add_f32 v[42:43], v[42:43], v[44:45]
	v_lshlrev_b32_e32 v44, 16, v146
	v_add_f32_e32 v28, v42, v43
	s_nop 1
	v_mov_b32_dpp v30, v28 quad_perm:[1,0,3,2] row_mask:0xf bank_mask:0xf
	v_and_b32_e32 v45, 0xffff0000, v146
	v_and_b32_e32 v47, 0xffff0000, v147
	s_waitcnt lgkmcnt(0)
	v_add_f32_e32 v28, v28, v30
	s_nop 1
	v_mov_b32_dpp v30, v28 quad_perm:[2,3,0,1] row_mask:0xf bank_mask:0xf
	s_waitcnt lgkmcnt(0)
	v_add_f32_e32 v28, v28, v30
	s_nop 1
	v_mov_b32_dpp v30, v28 row_half_mirror row_mask:0xf bank_mask:0xf
	s_waitcnt lgkmcnt(0)
	v_add_f32_e32 v28, v28, v30
	s_nop 1
	v_mov_b32_dpp v30, v28 row_mirror row_mask:0xf bank_mask:0xf
	s_waitcnt lgkmcnt(0)
	v_add_f32_e32 v28, v28, v30
	s_waitcnt lgkmcnt(0)
	s_nop 0
	v_readlane_b32 s98, v28, 32
	v_readlane_b32 s100, v28, 48
	s_nop 1
	v_mov_b32_e32 v30, s100
	v_add_f32_e32 v30, s98, v30
	v_readlane_b32 s98, v28, 0
	v_readlane_b32 s100, v28, 16
	s_nop 1
	v_mov_b32_e32 v28, s100
	v_add_f32_e32 v28, s98, v28
	v_add_f32_e32 v28, v28, v30
	s_waitcnt lgkmcnt(0)
	v_fmamk_f32 v28, v28, 0x3a800000, v247
	v_mul_f32_e32 v30, 0x4b800000, v28
	v_cmp_gt_f32_e32 vcc, s35, v28
	s_nop 1
	v_cndmask_b32_e32 v28, v28, v30, vcc
	v_rsq_f32_e32 v28, v28
	s_nop 0
	v_mul_f32_e32 v30, 0x45800000, v28
	v_cndmask_b32_e32 v42, v28, v30, vcc
	v_pk_mul_f32 v[16:17], v[42:43], v[16:17] op_sel_hi:[0,1]
	v_pk_mul_f32 v[18:19], v[42:43], v[18:19] op_sel_hi:[0,1]
	v_pk_fma_f32 v[18:19], v[88:89], v[18:19], v[46:47]
	v_pk_fma_f32 v[16:17], v[86:87], v[16:17], v[44:45]
	s_and_b64 vcc, exec, s[6:7]
	v_lshl_add_u64 v[44:45], v[134:135], 2, s[0:1]
	s_cbranch_vccnz .LBB0_847
	global_store_dwordx4 v[44:45], v[16:19], off sc0 sc1
	s_cbranch_execnz .LBB0_626
.LBB0_625:
	v_cvt_pk_bf16_f32 v46, v16, v17
	v_cvt_pk_bf16_f32 v47, v18, v19
	global_store_dwordx2 v[136:137], v[46:47], off sc0 sc1
.LBB0_626:
	v_mov_b32_e32 v43, v42
	v_lshlrev_b32_e32 v46, 16, v142
	v_and_b32_e32 v47, 0xffff0000, v142
	v_lshlrev_b32_e32 v48, 16, v143
	v_and_b32_e32 v49, 0xffff0000, v143
	v_mov_b32_e32 v142, v21
	v_mov_b32_e32 v143, v23
	v_mov_b32_e32 v146, v42
	v_mov_b32_e32 v147, v42
	v_mov_b32_e32 v21, v22
	v_pk_mul_f32 v[142:143], v[146:147], v[142:143]
	v_pk_mul_f32 v[20:21], v[42:43], v[20:21]
	v_pk_fma_f32 v[22:23], v[92:93], v[142:143], v[48:49]
	s_and_b64 vcc, exec, s[6:7]
	v_pk_fma_f32 v[20:21], v[90:91], v[20:21], v[46:47]
	s_cbranch_vccnz .LBB0_848
	global_store_dwordx4 v[44:45], v[20:23], off offset:1024 sc0 sc1
	s_cbranch_execnz .LBB0_629
.LBB0_628:
	v_cvt_pk_bf16_f32 v46, v20, v21
	v_cvt_pk_bf16_f32 v47, v22, v23
	global_store_dwordx2 v[136:137], v[46:47], off offset:512 sc0 sc1
.LBB0_629:
	v_lshlrev_b32_e32 v46, 16, v140
	v_and_b32_e32 v47, 0xffff0000, v140
	v_lshlrev_b32_e32 v48, 16, v141
	v_and_b32_e32 v49, 0xffff0000, v141
	v_mov_b32_e32 v140, v42
	v_mov_b32_e32 v141, v42
	v_pk_mul_f32 v[24:25], v[42:43], v[24:25]
	v_pk_mul_f32 v[26:27], v[140:141], v[26:27]
	s_and_b64 vcc, exec, s[6:7]
	v_pk_fma_f32 v[26:27], v[36:37], v[26:27], v[48:49]
	v_pk_fma_f32 v[24:25], v[32:33], v[24:25], v[46:47]
	s_cbranch_vccnz .LBB0_849
	global_store_dwordx4 v[44:45], v[24:27], off offset:2048 sc0 sc1
	s_cbranch_execnz .LBB0_632
.LBB0_631:
	v_cvt_pk_bf16_f32 v46, v24, v25
	v_cvt_pk_bf16_f32 v47, v26, v27
	global_store_dwordx2 v[136:137], v[46:47], off offset:1024 sc0 sc1
.LBB0_632:
	v_lshlrev_b32_e32 v46, 16, v138
	v_and_b32_e32 v47, 0xffff0000, v138
	v_lshlrev_b32_e32 v48, 16, v139
	v_and_b32_e32 v49, 0xffff0000, v139
	v_mov_b32_e32 v138, v42
	v_mov_b32_e32 v139, v42
	v_mov_b32_e32 v28, v31
	v_pk_mul_f32 v[40:41], v[40:41], v[138:139]
	v_pk_mul_f32 v[28:29], v[28:29], v[42:43]
	v_pk_fma_f32 v[30:31], v[38:39], v[40:41], v[48:49]
	s_and_b64 vcc, exec, s[6:7]
	v_pk_fma_f32 v[28:29], v[34:35], v[28:29], v[46:47]
	s_cbranch_vccnz .LBB0_850
	global_store_dwordx4 v[44:45], v[28:31], off offset:3072 sc0 sc1
	s_cbranch_execnz .LBB0_635
.LBB0_634:
	v_cvt_pk_bf16_f32 v40, v28, v29
	v_cvt_pk_bf16_f32 v41, v30, v31
	global_store_dwordx2 v[136:137], v[40:41], off offset:1536 sc0 sc1
.LBB0_635:
	s_and_b64 vcc, exec, s[4:5]
	s_cbranch_vccnz .LBB0_637
	v_mul_f32_e32 v40, v17, v17
	v_mul_f32_e32 v41, v19, v19
	v_fmac_f32_e32 v40, v16, v16
	v_fmac_f32_e32 v41, v18, v18
	v_add_f32_e32 v40, v40, v41
	v_mul_f32_e32 v41, v21, v21
	v_mul_f32_e32 v42, v23, v23
	v_fmac_f32_e32 v41, v20, v20
	v_fmac_f32_e32 v42, v22, v22
	v_add_f32_e32 v41, v41, v42
	v_add_f32_e32 v40, v40, v41
	v_mul_f32_e32 v41, v25, v25
	v_mul_f32_e32 v42, v27, v27
	v_fmac_f32_e32 v41, v24, v24
	v_fmac_f32_e32 v42, v26, v26
	v_add_f32_e32 v41, v41, v42
	v_add_f32_e32 v40, v41, v40
	v_mul_f32_e32 v41, v29, v29
	v_mul_f32_e32 v42, v31, v31
	v_fmac_f32_e32 v41, v28, v28
	v_fmac_f32_e32 v42, v30, v30
	v_add_f32_e32 v41, v41, v42
	v_add_f32_e32 v40, v41, v40
	s_nop 1
	v_mov_b32_dpp v41, v40 quad_perm:[1,0,3,2] row_mask:0xf bank_mask:0xf
	s_waitcnt lgkmcnt(0)
	v_add_f32_e32 v40, v40, v41
	s_nop 1
	v_mov_b32_dpp v41, v40 quad_perm:[2,3,0,1] row_mask:0xf bank_mask:0xf
	s_waitcnt lgkmcnt(0)
	v_add_f32_e32 v40, v40, v41
	s_nop 1
	v_mov_b32_dpp v41, v40 row_half_mirror row_mask:0xf bank_mask:0xf
	s_waitcnt lgkmcnt(0)
	v_add_f32_e32 v40, v40, v41
	s_nop 1
	v_mov_b32_dpp v41, v40 row_mirror row_mask:0xf bank_mask:0xf
	s_waitcnt lgkmcnt(0)
	v_add_f32_e32 v40, v40, v41
	s_waitcnt lgkmcnt(0)
	s_nop 0
	v_readlane_b32 s98, v40, 32
	v_readlane_b32 s100, v40, 48
	s_nop 1
	v_mov_b32_e32 v41, s100
	v_add_f32_e32 v41, s98, v41
	v_readlane_b32 s98, v40, 0
	v_readlane_b32 s100, v40, 16
	s_nop 1
	v_mov_b32_e32 v40, s100
	v_add_f32_e32 v40, s98, v40
	v_add_f32_e32 v40, v40, v41
	s_waitcnt lgkmcnt(0)
	v_fmamk_f32 v40, v40, 0x3a800000, v247
	v_mul_f32_e32 v41, 0x4b800000, v40
	v_cmp_gt_f32_e32 vcc, s35, v40
	s_nop 1
	v_cndmask_b32_e32 v40, v40, v41, vcc
	v_rsq_f32_e32 v42, v40
	v_lshl_add_u64 v[40:41], v[134:135], 1, s[42:43]
	v_mul_f32_e32 v43, 0x45800000, v42
	v_cndmask_b32_e32 v42, v42, v43, vcc
	v_pk_mul_f32 v[16:17], v[16:17], v[42:43] op_sel_hi:[1,0]
	v_pk_mul_f32 v[18:19], v[18:19], v[42:43] op_sel_hi:[1,0]
	v_pk_mul_f32 v[20:21], v[20:21], v[42:43] op_sel_hi:[1,0]
	v_pk_mul_f32 v[22:23], v[22:23], v[42:43] op_sel_hi:[1,0]
	v_pk_fma_f32 v[18:19], v[54:55], v[18:19], v[2:3]
	v_pk_fma_f32 v[16:17], v[52:53], v[16:17], v[0:1]
	v_pk_fma_f32 v[22:23], v[56:57], v[22:23], v[6:7]
	v_pk_fma_f32 v[20:21], v[50:51], v[20:21], v[4:5]
	v_cvt_pk_bf16_f32 v16, v16, v17
	v_cvt_pk_bf16_f32 v17, v18, v19
	v_cvt_pk_bf16_f32 v18, v20, v21
	v_cvt_pk_bf16_f32 v19, v22, v23
	global_store_dwordx2 v[40:41], v[16:17], off sc0 sc1
	global_store_dwordx2 v[40:41], v[18:19], off offset:512 sc0 sc1
	v_pk_mul_f32 v[16:17], v[24:25], v[42:43] op_sel_hi:[1,0]
	v_pk_mul_f32 v[18:19], v[26:27], v[42:43] op_sel_hi:[1,0]
	v_pk_fma_f32 v[16:17], v[60:61], v[16:17], v[8:9]
	v_pk_fma_f32 v[18:19], v[62:63], v[18:19], v[10:11]
	v_cvt_pk_bf16_f32 v16, v16, v17
	v_cvt_pk_bf16_f32 v17, v18, v19
	global_store_dwordx2 v[40:41], v[16:17], off offset:1024 sc0 sc1
	v_pk_mul_f32 v[16:17], v[28:29], v[42:43] op_sel_hi:[1,0]
	v_pk_mul_f32 v[18:19], v[30:31], v[42:43] op_sel_hi:[1,0]
	v_pk_fma_f32 v[16:17], v[58:59], v[16:17], v[12:13]
	v_pk_fma_f32 v[18:19], v[64:65], v[18:19], v[14:15]
	v_cvt_pk_bf16_f32 v16, v16, v17
	v_cvt_pk_bf16_f32 v17, v18, v19
	global_store_dwordx2 v[40:41], v[16:17], off offset:1536 sc0 sc1
.LBB0_637:
	v_and_b32_e32 v17, 0xffff0000, v132
	v_and_b32_e32 v19, 0xffff0000, v133
	v_lshlrev_b32_e32 v16, 16, v132
	v_lshlrev_b32_e32 v18, 16, v133
	v_mul_f32_e32 v20, v19, v19
	v_and_b32_e32 v23, 0xffff0000, v131
	v_and_b32_e32 v22, 0xffff0000, v130
	v_and_b32_e32 v29, 0xffff0000, v126
	v_mul_f32_e32 v28, v17, v17
	v_pk_fma_f32 v[42:43], v[18:19], v[18:19], v[20:21] op_sel_hi:[1,1,0]
	v_lshlrev_b32_e32 v21, 16, v131
	v_lshlrev_b32_e32 v20, 16, v130
	v_pk_mul_f32 v[24:25], v[22:23], v[22:23]
	v_lshlrev_b32_e32 v31, 16, v126
	v_pk_fma_f32 v[46:47], v[16:17], v[16:17], v[28:29] op_sel_hi:[1,1,0]
	v_pk_fma_f32 v[44:45], v[20:21], v[20:21], v[24:25]
	v_mov_b32_e32 v30, v46
	v_mov_b32_e32 v48, v42
	v_mov_b32_e32 v49, v31
	v_and_b32_e32 v25, 0xffff0000, v128
	v_mul_f32_e32 v126, v29, v29
	v_pk_add_f32 v[42:43], v[46:47], v[42:43]
	v_pk_mul_f32 v[46:47], v[30:31], v[48:49]
	v_pk_add_f32 v[44:45], v[44:45], v[44:45] op_sel:[0,1] op_sel_hi:[1,0]
	v_lshlrev_b32_e32 v24, 16, v128
	v_and_b32_e32 v27, 0xffff0000, v129
	v_mov_b32_e32 v43, v47
	v_mov_b32_e32 v45, v126
	v_mul_f32_e32 v28, v25, v25
	v_lshlrev_b32_e32 v26, 16, v129
	v_lshlrev_b32_e32 v40, 16, v127
	v_and_b32_e32 v41, 0xffff0000, v127
	v_pk_add_f32 v[42:43], v[42:43], v[44:45]
	v_pk_fma_f32 v[44:45], v[24:25], v[24:25], v[28:29] op_sel_hi:[1,1,0]
	v_mul_f32_e32 v28, v27, v27
	v_mul_f32_e32 v127, v40, v40
	v_mul_f32_e32 v128, v41, v41
	v_pk_fma_f32 v[46:47], v[26:27], v[26:27], v[28:29] op_sel_hi:[1,1,0]
	v_mov_b32_e32 v45, v127
	v_mov_b32_e32 v47, v128
	v_pk_add_f32 v[44:45], v[44:45], v[46:47]
	v_lshlrev_b32_e32 v46, 16, v125
	v_pk_add_f32 v[42:43], v[42:43], v[44:45]
	v_lshlrev_b32_e32 v44, 16, v124
	v_add_f32_e32 v28, v42, v43
	s_nop 1
	v_mov_b32_dpp v30, v28 quad_perm:[1,0,3,2] row_mask:0xf bank_mask:0xf
	v_and_b32_e32 v45, 0xffff0000, v124
	v_and_b32_e32 v47, 0xffff0000, v125
	s_waitcnt lgkmcnt(0)
	v_add_f32_e32 v28, v28, v30
	s_nop 1
	v_mov_b32_dpp v30, v28 quad_perm:[2,3,0,1] row_mask:0xf bank_mask:0xf
	s_waitcnt lgkmcnt(0)
	v_add_f32_e32 v28, v28, v30
	s_nop 1
	v_mov_b32_dpp v30, v28 row_half_mirror row_mask:0xf bank_mask:0xf
	s_waitcnt lgkmcnt(0)
	v_add_f32_e32 v28, v28, v30
	s_nop 1
	v_mov_b32_dpp v30, v28 row_mirror row_mask:0xf bank_mask:0xf
	s_waitcnt lgkmcnt(0)
	v_add_f32_e32 v28, v28, v30
	s_waitcnt lgkmcnt(0)
	s_nop 0
	v_readlane_b32 s98, v28, 32
	v_readlane_b32 s100, v28, 48
	s_nop 1
	v_mov_b32_e32 v30, s100
	v_add_f32_e32 v30, s98, v30
	v_readlane_b32 s98, v28, 0
	v_readlane_b32 s100, v28, 16
	s_nop 1
	v_mov_b32_e32 v28, s100
	v_add_f32_e32 v28, s98, v28
	v_add_f32_e32 v28, v28, v30
	s_waitcnt lgkmcnt(0)
	v_fmamk_f32 v28, v28, 0x3a800000, v247
	v_mul_f32_e32 v30, 0x4b800000, v28
	v_cmp_gt_f32_e32 vcc, s35, v28
	s_nop 1
	v_cndmask_b32_e32 v28, v28, v30, vcc
	v_rsq_f32_e32 v28, v28
	s_nop 0
	v_mul_f32_e32 v30, 0x45800000, v28
	v_cndmask_b32_e32 v42, v28, v30, vcc
	v_pk_mul_f32 v[16:17], v[42:43], v[16:17] op_sel_hi:[0,1]
	v_pk_mul_f32 v[18:19], v[42:43], v[18:19] op_sel_hi:[0,1]
	v_pk_fma_f32 v[18:19], v[88:89], v[18:19], v[46:47]
	v_pk_fma_f32 v[16:17], v[86:87], v[16:17], v[44:45]
	s_and_b64 vcc, exec, s[6:7]
	v_lshl_add_u64 v[44:45], v[114:115], 2, s[0:1]
	s_cbranch_vccnz .LBB0_851
	global_store_dwordx4 v[44:45], v[16:19], off sc0 sc1
	s_cbranch_execnz .LBB0_640
.LBB0_639:
	v_cvt_pk_bf16_f32 v46, v16, v17
	v_cvt_pk_bf16_f32 v47, v18, v19
	global_store_dwordx2 v[116:117], v[46:47], off sc0 sc1
.LBB0_640:
	v_mov_b32_e32 v43, v42
	v_lshlrev_b32_e32 v46, 16, v122
	v_and_b32_e32 v47, 0xffff0000, v122
	v_lshlrev_b32_e32 v48, 16, v123
	v_and_b32_e32 v49, 0xffff0000, v123
	v_mov_b32_e32 v122, v21
	v_mov_b32_e32 v123, v23
	v_mov_b32_e32 v124, v42
	v_mov_b32_e32 v125, v42
	v_mov_b32_e32 v21, v22
	v_pk_mul_f32 v[122:123], v[124:125], v[122:123]
	v_pk_mul_f32 v[20:21], v[42:43], v[20:21]
	v_pk_fma_f32 v[22:23], v[92:93], v[122:123], v[48:49]
	s_and_b64 vcc, exec, s[6:7]
	v_pk_fma_f32 v[20:21], v[90:91], v[20:21], v[46:47]
	s_cbranch_vccnz .LBB0_852
	global_store_dwordx4 v[44:45], v[20:23], off offset:1024 sc0 sc1
	s_cbranch_execnz .LBB0_643
.LBB0_642:
	v_cvt_pk_bf16_f32 v46, v20, v21
	v_cvt_pk_bf16_f32 v47, v22, v23
	global_store_dwordx2 v[116:117], v[46:47], off offset:512 sc0 sc1
.LBB0_643:
	v_lshlrev_b32_e32 v46, 16, v120
	v_and_b32_e32 v47, 0xffff0000, v120
	v_lshlrev_b32_e32 v48, 16, v121
	v_and_b32_e32 v49, 0xffff0000, v121
	v_mov_b32_e32 v120, v42
	v_mov_b32_e32 v121, v42
	v_pk_mul_f32 v[24:25], v[42:43], v[24:25]
	v_pk_mul_f32 v[26:27], v[120:121], v[26:27]
	s_and_b64 vcc, exec, s[6:7]
	v_pk_fma_f32 v[26:27], v[36:37], v[26:27], v[48:49]
	v_pk_fma_f32 v[24:25], v[32:33], v[24:25], v[46:47]
	s_cbranch_vccnz .LBB0_853
	global_store_dwordx4 v[44:45], v[24:27], off offset:2048 sc0 sc1
	s_cbranch_execnz .LBB0_646
.LBB0_645:
	v_cvt_pk_bf16_f32 v46, v24, v25
	v_cvt_pk_bf16_f32 v47, v26, v27
	global_store_dwordx2 v[116:117], v[46:47], off offset:1024 sc0 sc1
.LBB0_646:
	v_lshlrev_b32_e32 v46, 16, v118
	v_and_b32_e32 v47, 0xffff0000, v118
	v_lshlrev_b32_e32 v48, 16, v119
	v_and_b32_e32 v49, 0xffff0000, v119
	v_mov_b32_e32 v118, v42
	v_mov_b32_e32 v119, v42
	v_mov_b32_e32 v28, v31
	v_pk_mul_f32 v[40:41], v[40:41], v[118:119]
	v_pk_mul_f32 v[28:29], v[28:29], v[42:43]
	v_pk_fma_f32 v[30:31], v[38:39], v[40:41], v[48:49]
	s_and_b64 vcc, exec, s[6:7]
	v_pk_fma_f32 v[28:29], v[34:35], v[28:29], v[46:47]
	s_cbranch_vccnz .LBB0_854
	global_store_dwordx4 v[44:45], v[28:31], off offset:3072 sc0 sc1
	s_cbranch_execnz .LBB0_649
.LBB0_648:
	v_cvt_pk_bf16_f32 v40, v28, v29
	v_cvt_pk_bf16_f32 v41, v30, v31
	global_store_dwordx2 v[116:117], v[40:41], off offset:1536 sc0 sc1
.LBB0_649:
	s_and_b64 vcc, exec, s[4:5]
	s_cbranch_vccnz .LBB0_651
	v_mul_f32_e32 v40, v17, v17
	v_mul_f32_e32 v41, v19, v19
	v_fmac_f32_e32 v40, v16, v16
	v_fmac_f32_e32 v41, v18, v18
	v_add_f32_e32 v40, v40, v41
	v_mul_f32_e32 v41, v21, v21
	v_mul_f32_e32 v42, v23, v23
	v_fmac_f32_e32 v41, v20, v20
	v_fmac_f32_e32 v42, v22, v22
	v_add_f32_e32 v41, v41, v42
	v_add_f32_e32 v40, v40, v41
	v_mul_f32_e32 v41, v25, v25
	v_mul_f32_e32 v42, v27, v27
	v_fmac_f32_e32 v41, v24, v24
	v_fmac_f32_e32 v42, v26, v26
	v_add_f32_e32 v41, v41, v42
	v_add_f32_e32 v40, v41, v40
	v_mul_f32_e32 v41, v29, v29
	v_mul_f32_e32 v42, v31, v31
	v_fmac_f32_e32 v41, v28, v28
	v_fmac_f32_e32 v42, v30, v30
	v_add_f32_e32 v41, v41, v42
	v_add_f32_e32 v40, v41, v40
	s_nop 1
	v_mov_b32_dpp v41, v40 quad_perm:[1,0,3,2] row_mask:0xf bank_mask:0xf
	s_waitcnt lgkmcnt(0)
	v_add_f32_e32 v40, v40, v41
	s_nop 1
	v_mov_b32_dpp v41, v40 quad_perm:[2,3,0,1] row_mask:0xf bank_mask:0xf
	s_waitcnt lgkmcnt(0)
	v_add_f32_e32 v40, v40, v41
	s_nop 1
	v_mov_b32_dpp v41, v40 row_half_mirror row_mask:0xf bank_mask:0xf
	s_waitcnt lgkmcnt(0)
	v_add_f32_e32 v40, v40, v41
	s_nop 1
	v_mov_b32_dpp v41, v40 row_mirror row_mask:0xf bank_mask:0xf
	s_waitcnt lgkmcnt(0)
	v_add_f32_e32 v40, v40, v41
	s_waitcnt lgkmcnt(0)
	s_nop 0
	v_readlane_b32 s98, v40, 32
	v_readlane_b32 s100, v40, 48
	s_nop 1
	v_mov_b32_e32 v41, s100
	v_add_f32_e32 v41, s98, v41
	v_readlane_b32 s98, v40, 0
	v_readlane_b32 s100, v40, 16
	s_nop 1
	v_mov_b32_e32 v40, s100
	v_add_f32_e32 v40, s98, v40
	v_add_f32_e32 v40, v40, v41
	s_waitcnt lgkmcnt(0)
	v_fmamk_f32 v40, v40, 0x3a800000, v247
	v_mul_f32_e32 v41, 0x4b800000, v40
	v_cmp_gt_f32_e32 vcc, s35, v40
	s_nop 1
	v_cndmask_b32_e32 v40, v40, v41, vcc
	v_rsq_f32_e32 v42, v40
	v_lshl_add_u64 v[40:41], v[114:115], 1, s[42:43]
	v_mul_f32_e32 v43, 0x45800000, v42
	v_cndmask_b32_e32 v42, v42, v43, vcc
	v_pk_mul_f32 v[16:17], v[16:17], v[42:43] op_sel_hi:[1,0]
	v_pk_mul_f32 v[18:19], v[18:19], v[42:43] op_sel_hi:[1,0]
	v_pk_mul_f32 v[20:21], v[20:21], v[42:43] op_sel_hi:[1,0]
	v_pk_mul_f32 v[22:23], v[22:23], v[42:43] op_sel_hi:[1,0]
	v_pk_fma_f32 v[18:19], v[54:55], v[18:19], v[2:3]
	v_pk_fma_f32 v[16:17], v[52:53], v[16:17], v[0:1]
	v_pk_fma_f32 v[22:23], v[56:57], v[22:23], v[6:7]
	v_pk_fma_f32 v[20:21], v[50:51], v[20:21], v[4:5]
	v_cvt_pk_bf16_f32 v16, v16, v17
	v_cvt_pk_bf16_f32 v17, v18, v19
	v_cvt_pk_bf16_f32 v18, v20, v21
	v_cvt_pk_bf16_f32 v19, v22, v23
	global_store_dwordx2 v[40:41], v[16:17], off sc0 sc1
	global_store_dwordx2 v[40:41], v[18:19], off offset:512 sc0 sc1
	v_pk_mul_f32 v[16:17], v[24:25], v[42:43] op_sel_hi:[1,0]
	v_pk_mul_f32 v[18:19], v[26:27], v[42:43] op_sel_hi:[1,0]
	v_pk_fma_f32 v[16:17], v[60:61], v[16:17], v[8:9]
	v_pk_fma_f32 v[18:19], v[62:63], v[18:19], v[10:11]
	v_cvt_pk_bf16_f32 v16, v16, v17
	v_cvt_pk_bf16_f32 v17, v18, v19
	global_store_dwordx2 v[40:41], v[16:17], off offset:1024 sc0 sc1
	v_pk_mul_f32 v[16:17], v[28:29], v[42:43] op_sel_hi:[1,0]
	v_pk_mul_f32 v[18:19], v[30:31], v[42:43] op_sel_hi:[1,0]
	v_pk_fma_f32 v[16:17], v[58:59], v[16:17], v[12:13]
	v_pk_fma_f32 v[18:19], v[64:65], v[18:19], v[14:15]
	v_cvt_pk_bf16_f32 v16, v16, v17
	v_cvt_pk_bf16_f32 v17, v18, v19
	global_store_dwordx2 v[40:41], v[16:17], off offset:1536 sc0 sc1
.LBB0_651:
	v_and_b32_e32 v17, 0xffff0000, v112
	v_and_b32_e32 v19, 0xffff0000, v113
	v_lshlrev_b32_e32 v16, 16, v112
	v_lshlrev_b32_e32 v18, 16, v113
	v_mul_f32_e32 v20, v19, v19
	v_and_b32_e32 v23, 0xffff0000, v111
	v_and_b32_e32 v22, 0xffff0000, v110
	v_and_b32_e32 v29, 0xffff0000, v106
	v_mul_f32_e32 v28, v17, v17
	v_pk_fma_f32 v[42:43], v[18:19], v[18:19], v[20:21] op_sel_hi:[1,1,0]
	v_lshlrev_b32_e32 v21, 16, v111
	v_lshlrev_b32_e32 v20, 16, v110
	v_pk_mul_f32 v[24:25], v[22:23], v[22:23]
	v_lshlrev_b32_e32 v31, 16, v106
	v_pk_fma_f32 v[46:47], v[16:17], v[16:17], v[28:29] op_sel_hi:[1,1,0]
	v_pk_fma_f32 v[44:45], v[20:21], v[20:21], v[24:25]
	v_mov_b32_e32 v30, v46
	v_mov_b32_e32 v48, v42
	v_mov_b32_e32 v49, v31
	v_and_b32_e32 v25, 0xffff0000, v108
	v_mul_f32_e32 v106, v29, v29
	v_pk_add_f32 v[42:43], v[46:47], v[42:43]
	v_pk_mul_f32 v[46:47], v[30:31], v[48:49]
	v_pk_add_f32 v[44:45], v[44:45], v[44:45] op_sel:[0,1] op_sel_hi:[1,0]
	v_lshlrev_b32_e32 v24, 16, v108
	v_and_b32_e32 v27, 0xffff0000, v109
	v_mov_b32_e32 v43, v47
	v_mov_b32_e32 v45, v106
	v_mul_f32_e32 v28, v25, v25
	v_lshlrev_b32_e32 v26, 16, v109
	v_lshlrev_b32_e32 v40, 16, v107
	v_and_b32_e32 v41, 0xffff0000, v107
	v_pk_add_f32 v[42:43], v[42:43], v[44:45]
	v_pk_fma_f32 v[44:45], v[24:25], v[24:25], v[28:29] op_sel_hi:[1,1,0]
	v_mul_f32_e32 v28, v27, v27
	v_mul_f32_e32 v107, v40, v40
	v_mul_f32_e32 v108, v41, v41
	v_pk_fma_f32 v[46:47], v[26:27], v[26:27], v[28:29] op_sel_hi:[1,1,0]
	v_mov_b32_e32 v45, v107
	v_mov_b32_e32 v47, v108
	v_pk_add_f32 v[44:45], v[44:45], v[46:47]
	v_lshlrev_b32_e32 v46, 16, v105
	v_pk_add_f32 v[42:43], v[42:43], v[44:45]
	v_lshlrev_b32_e32 v44, 16, v104
	v_add_f32_e32 v28, v42, v43
	s_nop 1
	v_mov_b32_dpp v30, v28 quad_perm:[1,0,3,2] row_mask:0xf bank_mask:0xf
	v_and_b32_e32 v45, 0xffff0000, v104
	v_and_b32_e32 v47, 0xffff0000, v105
	s_waitcnt lgkmcnt(0)
	v_add_f32_e32 v28, v28, v30
	s_nop 1
	v_mov_b32_dpp v30, v28 quad_perm:[2,3,0,1] row_mask:0xf bank_mask:0xf
	s_waitcnt lgkmcnt(0)
	v_add_f32_e32 v28, v28, v30
	s_nop 1
	v_mov_b32_dpp v30, v28 row_half_mirror row_mask:0xf bank_mask:0xf
	s_waitcnt lgkmcnt(0)
	v_add_f32_e32 v28, v28, v30
	s_nop 1
	v_mov_b32_dpp v30, v28 row_mirror row_mask:0xf bank_mask:0xf
	s_waitcnt lgkmcnt(0)
	v_add_f32_e32 v28, v28, v30
	s_waitcnt lgkmcnt(0)
	s_nop 0
	v_readlane_b32 s98, v28, 32
	v_readlane_b32 s100, v28, 48
	s_nop 1
	v_mov_b32_e32 v30, s100
	v_add_f32_e32 v30, s98, v30
	v_readlane_b32 s98, v28, 0
	v_readlane_b32 s100, v28, 16
	s_nop 1
	v_mov_b32_e32 v28, s100
	v_add_f32_e32 v28, s98, v28
	v_add_f32_e32 v28, v28, v30
	s_waitcnt lgkmcnt(0)
	v_fmamk_f32 v28, v28, 0x3a800000, v247
	v_mul_f32_e32 v30, 0x4b800000, v28
	v_cmp_gt_f32_e32 vcc, s35, v28
	s_nop 1
	v_cndmask_b32_e32 v28, v28, v30, vcc
	v_rsq_f32_e32 v28, v28
	s_nop 0
	v_mul_f32_e32 v30, 0x45800000, v28
	v_cndmask_b32_e32 v42, v28, v30, vcc
	v_pk_mul_f32 v[16:17], v[42:43], v[16:17] op_sel_hi:[0,1]
	v_pk_mul_f32 v[18:19], v[42:43], v[18:19] op_sel_hi:[0,1]
	v_pk_fma_f32 v[18:19], v[88:89], v[18:19], v[46:47]
	v_pk_fma_f32 v[16:17], v[86:87], v[16:17], v[44:45]
	s_and_b64 vcc, exec, s[6:7]
	v_lshl_add_u64 v[44:45], v[94:95], 2, s[0:1]
	s_cbranch_vccnz .LBB0_855
	global_store_dwordx4 v[44:45], v[16:19], off sc0 sc1
	s_cbranch_execnz .LBB0_654
.LBB0_653:
	v_cvt_pk_bf16_f32 v46, v16, v17
	v_cvt_pk_bf16_f32 v47, v18, v19
	global_store_dwordx2 v[96:97], v[46:47], off sc0 sc1
.LBB0_654:
	v_mov_b32_e32 v43, v42
	v_lshlrev_b32_e32 v46, 16, v102
	v_and_b32_e32 v47, 0xffff0000, v102
	v_lshlrev_b32_e32 v48, 16, v103
	v_and_b32_e32 v49, 0xffff0000, v103
	v_mov_b32_e32 v102, v21
	v_mov_b32_e32 v103, v23
	v_mov_b32_e32 v104, v42
	v_mov_b32_e32 v105, v42
	v_mov_b32_e32 v21, v22
	v_pk_mul_f32 v[102:103], v[104:105], v[102:103]
	v_pk_mul_f32 v[20:21], v[42:43], v[20:21]
	v_pk_fma_f32 v[22:23], v[92:93], v[102:103], v[48:49]
	s_and_b64 vcc, exec, s[6:7]
	v_pk_fma_f32 v[20:21], v[90:91], v[20:21], v[46:47]
	s_cbranch_vccnz .LBB0_856
	global_store_dwordx4 v[44:45], v[20:23], off offset:1024 sc0 sc1
	s_cbranch_execnz .LBB0_657
.LBB0_656:
	v_cvt_pk_bf16_f32 v46, v20, v21
	v_cvt_pk_bf16_f32 v47, v22, v23
	global_store_dwordx2 v[96:97], v[46:47], off offset:512 sc0 sc1
.LBB0_657:
	v_lshlrev_b32_e32 v46, 16, v100
	v_and_b32_e32 v47, 0xffff0000, v100
	v_lshlrev_b32_e32 v48, 16, v101
	v_and_b32_e32 v49, 0xffff0000, v101
	v_mov_b32_e32 v100, v42
	v_mov_b32_e32 v101, v42
	v_pk_mul_f32 v[24:25], v[42:43], v[24:25]
	v_pk_mul_f32 v[26:27], v[100:101], v[26:27]
	s_and_b64 vcc, exec, s[6:7]
	v_pk_fma_f32 v[26:27], v[36:37], v[26:27], v[48:49]
	v_pk_fma_f32 v[24:25], v[32:33], v[24:25], v[46:47]
	s_cbranch_vccnz .LBB0_857
	global_store_dwordx4 v[44:45], v[24:27], off offset:2048 sc0 sc1
	s_cbranch_execnz .LBB0_660
.LBB0_659:
	v_cvt_pk_bf16_f32 v46, v24, v25
	v_cvt_pk_bf16_f32 v47, v26, v27
	global_store_dwordx2 v[96:97], v[46:47], off offset:1024 sc0 sc1
.LBB0_660:
	v_lshlrev_b32_e32 v46, 16, v98
	v_and_b32_e32 v47, 0xffff0000, v98
	v_lshlrev_b32_e32 v48, 16, v99
	v_and_b32_e32 v49, 0xffff0000, v99
	v_mov_b32_e32 v98, v42
	v_mov_b32_e32 v99, v42
	v_mov_b32_e32 v28, v31
	v_pk_mul_f32 v[40:41], v[40:41], v[98:99]
	v_pk_mul_f32 v[28:29], v[28:29], v[42:43]
	v_pk_fma_f32 v[30:31], v[38:39], v[40:41], v[48:49]
	s_and_b64 vcc, exec, s[6:7]
	v_pk_fma_f32 v[28:29], v[34:35], v[28:29], v[46:47]
	s_cbranch_vccnz .LBB0_858
	global_store_dwordx4 v[44:45], v[28:31], off offset:3072 sc0 sc1
	s_cbranch_execnz .LBB0_663
.LBB0_662:
	v_cvt_pk_bf16_f32 v40, v28, v29
	v_cvt_pk_bf16_f32 v41, v30, v31
	global_store_dwordx2 v[96:97], v[40:41], off offset:1536 sc0 sc1
.LBB0_663:
	s_and_b64 vcc, exec, s[4:5]
	s_cbranch_vccnz .LBB0_665
	v_mul_f32_e32 v40, v17, v17
	v_mul_f32_e32 v41, v19, v19
	v_fmac_f32_e32 v40, v16, v16
	v_fmac_f32_e32 v41, v18, v18
	v_add_f32_e32 v40, v40, v41
	v_mul_f32_e32 v41, v21, v21
	v_mul_f32_e32 v42, v23, v23
	v_fmac_f32_e32 v41, v20, v20
	v_fmac_f32_e32 v42, v22, v22
	v_add_f32_e32 v41, v41, v42
	v_add_f32_e32 v40, v40, v41
	v_mul_f32_e32 v41, v25, v25
	v_mul_f32_e32 v42, v27, v27
	v_fmac_f32_e32 v41, v24, v24
	v_fmac_f32_e32 v42, v26, v26
	v_add_f32_e32 v41, v41, v42
	v_add_f32_e32 v40, v41, v40
	v_mul_f32_e32 v41, v29, v29
	v_mul_f32_e32 v42, v31, v31
	v_fmac_f32_e32 v41, v28, v28
	v_fmac_f32_e32 v42, v30, v30
	v_add_f32_e32 v41, v41, v42
	v_add_f32_e32 v40, v41, v40
	s_nop 1
	v_mov_b32_dpp v41, v40 quad_perm:[1,0,3,2] row_mask:0xf bank_mask:0xf
	s_waitcnt lgkmcnt(0)
	v_add_f32_e32 v40, v40, v41
	s_nop 1
	v_mov_b32_dpp v41, v40 quad_perm:[2,3,0,1] row_mask:0xf bank_mask:0xf
	s_waitcnt lgkmcnt(0)
	v_add_f32_e32 v40, v40, v41
	s_nop 1
	v_mov_b32_dpp v41, v40 row_half_mirror row_mask:0xf bank_mask:0xf
	s_waitcnt lgkmcnt(0)
	v_add_f32_e32 v40, v40, v41
	s_nop 1
	v_mov_b32_dpp v41, v40 row_mirror row_mask:0xf bank_mask:0xf
	s_waitcnt lgkmcnt(0)
	v_add_f32_e32 v40, v40, v41
	s_waitcnt lgkmcnt(0)
	s_nop 0
	v_readlane_b32 s98, v40, 32
	v_readlane_b32 s100, v40, 48
	s_nop 1
	v_mov_b32_e32 v41, s100
	v_add_f32_e32 v41, s98, v41
	v_readlane_b32 s98, v40, 0
	v_readlane_b32 s100, v40, 16
	s_nop 1
	v_mov_b32_e32 v40, s100
	v_add_f32_e32 v40, s98, v40
	v_add_f32_e32 v40, v40, v41
	s_waitcnt lgkmcnt(0)
	v_fmamk_f32 v40, v40, 0x3a800000, v247
	v_mul_f32_e32 v41, 0x4b800000, v40
	v_cmp_gt_f32_e32 vcc, s35, v40
	s_nop 1
	v_cndmask_b32_e32 v40, v40, v41, vcc
	v_rsq_f32_e32 v42, v40
	v_lshl_add_u64 v[40:41], v[94:95], 1, s[42:43]
	v_mul_f32_e32 v43, 0x45800000, v42
	v_cndmask_b32_e32 v42, v42, v43, vcc
	v_pk_mul_f32 v[16:17], v[16:17], v[42:43] op_sel_hi:[1,0]
	v_pk_mul_f32 v[18:19], v[18:19], v[42:43] op_sel_hi:[1,0]
	v_pk_mul_f32 v[20:21], v[20:21], v[42:43] op_sel_hi:[1,0]
	v_pk_mul_f32 v[22:23], v[22:23], v[42:43] op_sel_hi:[1,0]
	v_pk_fma_f32 v[18:19], v[54:55], v[18:19], v[2:3]
	v_pk_fma_f32 v[16:17], v[52:53], v[16:17], v[0:1]
	v_pk_fma_f32 v[22:23], v[56:57], v[22:23], v[6:7]
	v_pk_fma_f32 v[20:21], v[50:51], v[20:21], v[4:5]
	v_cvt_pk_bf16_f32 v16, v16, v17
	v_cvt_pk_bf16_f32 v17, v18, v19
	v_cvt_pk_bf16_f32 v18, v20, v21
	v_cvt_pk_bf16_f32 v19, v22, v23
	global_store_dwordx2 v[40:41], v[16:17], off sc0 sc1
	global_store_dwordx2 v[40:41], v[18:19], off offset:512 sc0 sc1
	v_pk_mul_f32 v[16:17], v[24:25], v[42:43] op_sel_hi:[1,0]
	v_pk_mul_f32 v[18:19], v[26:27], v[42:43] op_sel_hi:[1,0]
	v_pk_fma_f32 v[16:17], v[60:61], v[16:17], v[8:9]
	v_pk_fma_f32 v[18:19], v[62:63], v[18:19], v[10:11]
	v_cvt_pk_bf16_f32 v16, v16, v17
	v_cvt_pk_bf16_f32 v17, v18, v19
	global_store_dwordx2 v[40:41], v[16:17], off offset:1024 sc0 sc1
	v_pk_mul_f32 v[16:17], v[28:29], v[42:43] op_sel_hi:[1,0]
	v_pk_mul_f32 v[18:19], v[30:31], v[42:43] op_sel_hi:[1,0]
	v_pk_fma_f32 v[16:17], v[58:59], v[16:17], v[12:13]
	v_pk_fma_f32 v[18:19], v[64:65], v[18:19], v[14:15]
	v_cvt_pk_bf16_f32 v16, v16, v17
	v_cvt_pk_bf16_f32 v17, v18, v19
	global_store_dwordx2 v[40:41], v[16:17], off offset:1536 sc0 sc1
.LBB0_665:
	v_and_b32_e32 v17, 0xffff0000, v84
	v_and_b32_e32 v19, 0xffff0000, v85
	v_lshlrev_b32_e32 v16, 16, v84
	v_lshlrev_b32_e32 v18, 16, v85
	v_mul_f32_e32 v20, v19, v19
	v_and_b32_e32 v23, 0xffff0000, v83
	v_and_b32_e32 v22, 0xffff0000, v82
	v_and_b32_e32 v29, 0xffff0000, v78
	v_mul_f32_e32 v28, v17, v17
	v_pk_fma_f32 v[42:43], v[18:19], v[18:19], v[20:21] op_sel_hi:[1,1,0]
	v_lshlrev_b32_e32 v21, 16, v83
	v_lshlrev_b32_e32 v20, 16, v82
	v_pk_mul_f32 v[24:25], v[22:23], v[22:23]
	v_lshlrev_b32_e32 v31, 16, v78
	v_pk_fma_f32 v[46:47], v[16:17], v[16:17], v[28:29] op_sel_hi:[1,1,0]
	v_pk_fma_f32 v[44:45], v[20:21], v[20:21], v[24:25]
	v_mov_b32_e32 v30, v46
	v_mov_b32_e32 v48, v42
	v_mov_b32_e32 v49, v31
	v_and_b32_e32 v25, 0xffff0000, v80
	v_mul_f32_e32 v78, v29, v29
	v_pk_add_f32 v[42:43], v[46:47], v[42:43]
	v_pk_mul_f32 v[46:47], v[30:31], v[48:49]
	v_pk_add_f32 v[44:45], v[44:45], v[44:45] op_sel:[0,1] op_sel_hi:[1,0]
	v_lshlrev_b32_e32 v24, 16, v80
	v_and_b32_e32 v27, 0xffff0000, v81
	v_mov_b32_e32 v43, v47
	v_mov_b32_e32 v45, v78
	v_mul_f32_e32 v28, v25, v25
	v_lshlrev_b32_e32 v26, 16, v81
	v_lshlrev_b32_e32 v40, 16, v79
	v_and_b32_e32 v41, 0xffff0000, v79
	v_pk_add_f32 v[42:43], v[42:43], v[44:45]
	v_pk_fma_f32 v[44:45], v[24:25], v[24:25], v[28:29] op_sel_hi:[1,1,0]
	v_mul_f32_e32 v28, v27, v27
	v_mul_f32_e32 v79, v40, v40
	v_mul_f32_e32 v80, v41, v41
	v_pk_fma_f32 v[46:47], v[26:27], v[26:27], v[28:29] op_sel_hi:[1,1,0]
	v_mov_b32_e32 v45, v79
	v_mov_b32_e32 v47, v80
	v_pk_add_f32 v[44:45], v[44:45], v[46:47]
	v_lshlrev_b32_e32 v46, 16, v77
	v_pk_add_f32 v[42:43], v[42:43], v[44:45]
	v_lshlrev_b32_e32 v44, 16, v76
	v_add_f32_e32 v28, v42, v43
	s_nop 1
	v_mov_b32_dpp v30, v28 quad_perm:[1,0,3,2] row_mask:0xf bank_mask:0xf
	v_and_b32_e32 v45, 0xffff0000, v76
	v_and_b32_e32 v47, 0xffff0000, v77
	s_waitcnt lgkmcnt(0)
	v_add_f32_e32 v28, v28, v30
	s_nop 1
	v_mov_b32_dpp v30, v28 quad_perm:[2,3,0,1] row_mask:0xf bank_mask:0xf
	s_waitcnt lgkmcnt(0)
	v_add_f32_e32 v28, v28, v30
	s_nop 1
	v_mov_b32_dpp v30, v28 row_half_mirror row_mask:0xf bank_mask:0xf
	s_waitcnt lgkmcnt(0)
	v_add_f32_e32 v28, v28, v30
	s_nop 1
	v_mov_b32_dpp v30, v28 row_mirror row_mask:0xf bank_mask:0xf
	s_waitcnt lgkmcnt(0)
	v_add_f32_e32 v28, v28, v30
	s_waitcnt lgkmcnt(0)
	s_nop 0
	v_readlane_b32 s98, v28, 32
	v_readlane_b32 s100, v28, 48
	s_nop 1
	v_mov_b32_e32 v30, s100
	v_add_f32_e32 v30, s98, v30
	v_readlane_b32 s98, v28, 0
	v_readlane_b32 s100, v28, 16
	s_nop 1
	v_mov_b32_e32 v28, s100
	v_add_f32_e32 v28, s98, v28
	v_add_f32_e32 v28, v28, v30
	s_waitcnt lgkmcnt(0)
	v_fmamk_f32 v28, v28, 0x3a800000, v247
	v_mul_f32_e32 v30, 0x4b800000, v28
	v_cmp_gt_f32_e32 vcc, s35, v28
	s_nop 1
	v_cndmask_b32_e32 v28, v28, v30, vcc
	v_rsq_f32_e32 v28, v28
	s_nop 0
	v_mul_f32_e32 v30, 0x45800000, v28
	v_cndmask_b32_e32 v42, v28, v30, vcc
	v_pk_mul_f32 v[16:17], v[42:43], v[16:17] op_sel_hi:[0,1]
	v_pk_mul_f32 v[18:19], v[42:43], v[18:19] op_sel_hi:[0,1]
	v_pk_fma_f32 v[18:19], v[88:89], v[18:19], v[46:47]
	v_pk_fma_f32 v[16:17], v[86:87], v[16:17], v[44:45]
	s_and_b64 vcc, exec, s[6:7]
	v_lshl_add_u64 v[44:45], v[66:67], 2, s[0:1]
	s_cbranch_vccnz .LBB0_859
	global_store_dwordx4 v[44:45], v[16:19], off sc0 sc1
	s_cbranch_execnz .LBB0_668
.LBB0_667:
	v_cvt_pk_bf16_f32 v46, v16, v17
	v_cvt_pk_bf16_f32 v47, v18, v19
	global_store_dwordx2 v[68:69], v[46:47], off sc0 sc1
.LBB0_668:
	v_mov_b32_e32 v43, v42
	v_lshlrev_b32_e32 v46, 16, v74
	v_and_b32_e32 v47, 0xffff0000, v74
	v_lshlrev_b32_e32 v48, 16, v75
	v_and_b32_e32 v49, 0xffff0000, v75
	v_mov_b32_e32 v74, v21
	v_mov_b32_e32 v75, v23
	v_mov_b32_e32 v76, v42
	v_mov_b32_e32 v77, v42
	v_mov_b32_e32 v21, v22
	v_pk_mul_f32 v[74:75], v[76:77], v[74:75]
	v_pk_mul_f32 v[20:21], v[42:43], v[20:21]
	v_pk_fma_f32 v[22:23], v[92:93], v[74:75], v[48:49]
	s_and_b64 vcc, exec, s[6:7]
	v_pk_fma_f32 v[20:21], v[90:91], v[20:21], v[46:47]
	s_cbranch_vccnz .LBB0_860
	global_store_dwordx4 v[44:45], v[20:23], off offset:1024 sc0 sc1
	s_cbranch_execnz .LBB0_671
.LBB0_670:
	v_cvt_pk_bf16_f32 v46, v20, v21
	v_cvt_pk_bf16_f32 v47, v22, v23
	global_store_dwordx2 v[68:69], v[46:47], off offset:512 sc0 sc1
.LBB0_671:
	v_lshlrev_b32_e32 v46, 16, v72
	v_and_b32_e32 v47, 0xffff0000, v72
	v_lshlrev_b32_e32 v48, 16, v73
	v_and_b32_e32 v49, 0xffff0000, v73
	v_mov_b32_e32 v72, v42
	v_mov_b32_e32 v73, v42
	v_pk_mul_f32 v[24:25], v[42:43], v[24:25]
	v_pk_mul_f32 v[26:27], v[72:73], v[26:27]
	s_and_b64 vcc, exec, s[6:7]
	v_pk_fma_f32 v[26:27], v[36:37], v[26:27], v[48:49]
	v_pk_fma_f32 v[24:25], v[32:33], v[24:25], v[46:47]
	s_cbranch_vccnz .LBB0_861
	global_store_dwordx4 v[44:45], v[24:27], off offset:2048 sc0 sc1
	s_cbranch_execnz .LBB0_674
.LBB0_673:
	v_cvt_pk_bf16_f32 v32, v24, v25
	v_cvt_pk_bf16_f32 v33, v26, v27
	global_store_dwordx2 v[68:69], v[32:33], off offset:1024 sc0 sc1
.LBB0_674:
	v_mov_b32_e32 v46, v42
	v_mov_b32_e32 v47, v42
	v_mov_b32_e32 v28, v31
	v_lshlrev_b32_e32 v32, 16, v70
	v_and_b32_e32 v33, 0xffff0000, v70
	v_lshlrev_b32_e32 v36, 16, v71
	v_and_b32_e32 v37, 0xffff0000, v71
	v_pk_mul_f32 v[40:41], v[40:41], v[46:47]
	v_pk_mul_f32 v[28:29], v[28:29], v[42:43]
	v_pk_fma_f32 v[30:31], v[38:39], v[40:41], v[36:37]
	s_and_b64 vcc, exec, s[6:7]
	v_pk_fma_f32 v[28:29], v[34:35], v[28:29], v[32:33]
	s_cbranch_vccnz .LBB0_862
	global_store_dwordx4 v[44:45], v[28:31], off offset:3072 sc0 sc1
	s_cbranch_execnz .LBB0_677
.LBB0_676:
	v_cvt_pk_bf16_f32 v32, v28, v29
	v_cvt_pk_bf16_f32 v33, v30, v31
	global_store_dwordx2 v[68:69], v[32:33], off offset:1536 sc0 sc1
.LBB0_677:
	s_and_b64 vcc, exec, s[4:5]
	s_cbranch_vccnz .LBB0_679
	v_mul_f32_e32 v32, v17, v17
	v_mul_f32_e32 v33, v19, v19
	v_fmac_f32_e32 v32, v16, v16
	v_fmac_f32_e32 v33, v18, v18
	v_add_f32_e32 v32, v32, v33
	v_mul_f32_e32 v33, v21, v21
	v_mul_f32_e32 v34, v23, v23
	v_fmac_f32_e32 v33, v20, v20
	v_fmac_f32_e32 v34, v22, v22
	v_add_f32_e32 v33, v33, v34
	v_add_f32_e32 v32, v32, v33
	v_mul_f32_e32 v33, v25, v25
	v_mul_f32_e32 v34, v27, v27
	v_fmac_f32_e32 v33, v24, v24
	v_fmac_f32_e32 v34, v26, v26
	v_add_f32_e32 v33, v33, v34
	v_add_f32_e32 v32, v33, v32
	v_mul_f32_e32 v33, v29, v29
	v_mul_f32_e32 v34, v31, v31
	v_fmac_f32_e32 v33, v28, v28
	v_fmac_f32_e32 v34, v30, v30
	v_add_f32_e32 v33, v33, v34
	v_add_f32_e32 v32, v33, v32
	s_nop 1
	v_mov_b32_dpp v33, v32 quad_perm:[1,0,3,2] row_mask:0xf bank_mask:0xf
	s_mov_b64 s[4:5], 0
	s_waitcnt lgkmcnt(0)
	v_add_f32_e32 v32, v32, v33
	s_nop 1
	v_mov_b32_dpp v33, v32 quad_perm:[2,3,0,1] row_mask:0xf bank_mask:0xf
	s_waitcnt lgkmcnt(0)
	v_add_f32_e32 v32, v32, v33
	s_nop 1
	v_mov_b32_dpp v33, v32 row_half_mirror row_mask:0xf bank_mask:0xf
	s_waitcnt lgkmcnt(0)
	v_add_f32_e32 v32, v32, v33
	s_nop 1
	v_mov_b32_dpp v33, v32 row_mirror row_mask:0xf bank_mask:0xf
	s_waitcnt lgkmcnt(0)
	v_add_f32_e32 v32, v32, v33
	s_waitcnt lgkmcnt(0)
	s_nop 0
	v_readlane_b32 s98, v32, 32
	v_readlane_b32 s100, v32, 48
	s_nop 1
	v_mov_b32_e32 v33, s100
	v_add_f32_e32 v33, s98, v33
	v_readlane_b32 s98, v32, 0
	v_readlane_b32 s100, v32, 16
	s_nop 1
	v_mov_b32_e32 v32, s100
	v_add_f32_e32 v32, s98, v32
	v_add_f32_e32 v32, v32, v33
	s_waitcnt lgkmcnt(0)
	v_fmamk_f32 v32, v32, 0x3a800000, v247
	v_mul_f32_e32 v33, 0x4b800000, v32
	v_cmp_gt_f32_e32 vcc, s35, v32
	s_nop 1
	v_cndmask_b32_e32 v32, v32, v33, vcc
	v_rsq_f32_e32 v34, v32
	v_lshl_add_u64 v[32:33], v[66:67], 1, s[42:43]
	v_mul_f32_e32 v35, 0x45800000, v34
	v_cndmask_b32_e32 v34, v34, v35, vcc
	v_pk_mul_f32 v[16:17], v[16:17], v[34:35] op_sel_hi:[1,0]
	v_pk_mul_f32 v[18:19], v[18:19], v[34:35] op_sel_hi:[1,0]
	v_pk_mul_f32 v[20:21], v[20:21], v[34:35] op_sel_hi:[1,0]
	v_pk_mul_f32 v[22:23], v[22:23], v[34:35] op_sel_hi:[1,0]
	v_pk_fma_f32 v[2:3], v[54:55], v[18:19], v[2:3]
	v_pk_fma_f32 v[0:1], v[52:53], v[16:17], v[0:1]
	v_pk_fma_f32 v[6:7], v[56:57], v[22:23], v[6:7]
	v_pk_fma_f32 v[4:5], v[50:51], v[20:21], v[4:5]
	v_cvt_pk_bf16_f32 v0, v0, v1
	v_cvt_pk_bf16_f32 v1, v2, v3
	v_cvt_pk_bf16_f32 v2, v4, v5
	v_cvt_pk_bf16_f32 v3, v6, v7
	global_store_dwordx2 v[32:33], v[0:1], off sc0 sc1
	global_store_dwordx2 v[32:33], v[2:3], off offset:512 sc0 sc1
	v_pk_mul_f32 v[0:1], v[24:25], v[34:35] op_sel_hi:[1,0]
	v_pk_mul_f32 v[2:3], v[26:27], v[34:35] op_sel_hi:[1,0]
	v_pk_fma_f32 v[0:1], v[60:61], v[0:1], v[8:9]
	v_pk_fma_f32 v[2:3], v[62:63], v[2:3], v[10:11]
	v_cvt_pk_bf16_f32 v0, v0, v1
	v_cvt_pk_bf16_f32 v1, v2, v3
	global_store_dwordx2 v[32:33], v[0:1], off offset:1024 sc0 sc1
	v_pk_mul_f32 v[0:1], v[28:29], v[34:35] op_sel_hi:[1,0]
	v_pk_mul_f32 v[2:3], v[30:31], v[34:35] op_sel_hi:[1,0]
	v_pk_fma_f32 v[0:1], v[58:59], v[0:1], v[12:13]
	v_pk_fma_f32 v[2:3], v[64:65], v[2:3], v[14:15]
	v_cvt_pk_bf16_f32 v0, v0, v1
	v_cvt_pk_bf16_f32 v1, v2, v3
	global_store_dwordx2 v[32:33], v[0:1], off offset:1536 sc0 sc1
	s_branch .LBB0_680
